# hand-written P11: all loads of each section in flight before the first wait; sample rows as a sliding window per (sequence, 8 channels)
# speedup vs baseline: 1.0221x; 1.0029x over previous
; __device__ __forceinline__ void phase_ffnconv(const Params& p) {
;     ...
;     for (int it = gt; it < 128 * 2 * NCH; it += NGT) {
;         const int c = it % NCH, q = it / NCH, sl = q & 1, blk = q >> 1, j0 = 8 * c, colg = (j0 >> 7) * 256 + (j0 & 127);
;         const int row = blk * 64 + sl; const bool first = (blk & 31) == 0;
;         float wg[3][8], wv[3][8], ag[8], av[8];
; #pragma unroll
;         for (int k = 0; k < 3; ++k) { ld8f(p.in[I_WFCONV] + (size_t)k * 2 * DFF + j0, wg[k]); ld8f(p.in[I_WFCONV] + (size_t)k * 2 * DFF + DFF + j0, wv[k]); }
;         ld8f(p.in[I_BFCONV] + j0, ag); ld8f(p.in[I_BFCONV] + DFF + j0, av);
;     ...
;     for (int i = gt; i < NSEQ * 2 * (2 * DFF / 8); i += NGT) { const int c = i % 1536, q = i / 1536, r = q & 1, s = q >> 1, n0 = 8 * c;
;         const int j0 = n0 < DFF ? n0 : n0 - DFF, col = (j0 >> 7) * 256 + (n0 < DFF ? 0 : 128) + (j0 & 127);
;         const int row = s < 4 ? s * SEQ + SEQ - 2 + r : MPROMPT + (s - 4) * 8 + 6 + r;
;         float x[8];
;         if (s < 4) unpack8(*(const u32x4*)(UPB + ((size_t)(s * 32 + 31) * 4 + 2 + r) * (2 * DFF) + col), x); else unpack8(*(const u32x4*)(UP + (size_t)row * 2 * DFF + col), x);
;         float* o = p.out + (s < 4 ? O_FCONVP + ((size_t)s * 2 + r) * 2 * DFF : O_FCONVS + ((size_t)(s - 4) * 2 + r) * 2 * DFF) + n0;
;         __builtin_nontemporal_store((f32x4){x[0], x[1], x[2], x[3]}, (f32x4*)o); __builtin_nontemporal_store((f32x4){x[4], x[5], x[6], x[7]}, (f32x4*)(o + 4)); }
.Lipf_skip_10:
	s_mov_b32 s0, 0x30000
	v_cmp_gt_i32_e32 vcc, s0, v220
	s_waitcnt lgkmcnt(0)
	s_barrier
	v_and_b32_e32 v0, 63, v220
	v_readfirstlane_b32 s0, v220
	v_readlane_b32 s10, v254, 41
	v_readlane_b32 s11, v254, 42
	v_readlane_b32 s12, v254, 43
	v_readlane_b32 s13, v254, 44
	v_readlane_b32 s14, v254, 15
	v_readlane_b32 s15, v254, 16
	v_readlane_b32 s16, v254, 47
	v_readlane_b32 s17, v254, 48
	v_lshrrev_b32_e32 v2, 4, v0
	v_and_b32_e32 v3, 15, v0
	v_lshlrev_b32_e32 v2, 9, v2
	v_lshl_or_b32 v1, v3, 4, v2
	v_lshlrev_b32_e32 v2, 5, v0
	v_lshlrev_b32_e32 v3, 4, v0
	v_mov_b32_e32 v4, 0xc0135761
	v_mov_b32_e32 v5, 0xc0135761
	s_mov_b32 s26, 0xbdd2d3e8
	s_mov_b32 s27, 0xbdd2d3e8
	s_mov_b32 s28, 1.0
	s_mov_b32 s29, 1.0
	s_add_u32 s18, s84, 0x9100000
	s_addc_u32 s19, s85, 0
	s_add_u32 s20, s84, 0x19d00000
	s_addc_u32 s21, s85, 0
	s_add_u32 s22, s84, 0xdd00000
	s_addc_u32 s23, s85, 0
	s_cmp_lt_u32 s0, 0x3000
	s_cselect_b32 s64, 1, 0
	s_add_i32 s4, s0, 0x0
	s_lshr_b32 s5, s4, 9
	s_mul_i32 s5, s5, 0xaaab
	s_lshr_b32 s5, s5, 17
	s_mul_i32 s6, s5, 0x600
	s_sub_i32 s6, s4, s6
	s_cmp_ge_u32 s6, 0x300
	s_cselect_b32 s7, 0x300, 0
	s_cselect_b32 s35, 0x100, 0
	s_sub_i32 s7, s6, s7
	s_lshl_b32 s7, s7, 5
	s_add_i32 s7, s7, s35
	s_and_b32 s50, s5, 1
	s_lshr_b32 s51, s5, 1
	s_lshl_b32 s52, s51, 7
	s_add_i32 s52, s52, 0x7e
	s_add_i32 s52, s52, s50
	s_lshl_b32 s53, s51, 3
	s_add_i32 s53, s53, s50
	s_sub_i32 s53, s53, 26
	s_cmp_lt_u32 s51, 4
	s_cselect_b32 s52, s52, s53
	s_cselect_b32 s54, s18, s20
	s_cselect_b32 s55, s19, s21
	s_mov_b32 s53, 0x53dc000
	s_cselect_b32 s53, 0x485c000, s53
	s_mul_i32 s52, s52, 0x6000
	s_add_i32 s52, s52, s7
	s_add_u32 s54, s54, s52
	s_addc_u32 s55, s55, 0
	global_load_dwordx4 v[8:11], v1, s[54:55]
	s_mul_i32 s52, s5, 0xc000
	s_add_u32 s52, s52, s53
	s_lshl_b32 s6, s6, 5
	s_add_u32 s52, s52, s6
	s_add_u32 s56, s16, s52
	s_addc_u32 s57, s17, 0
	s_add_i32 s4, s0, 0x20000
	s_lshr_b32 s5, s4, 9
	s_mul_i32 s5, s5, 0xaaab
	s_lshr_b32 s5, s5, 17
	s_mul_i32 s6, s5, 0x600
	s_sub_i32 s6, s4, s6
	s_cmp_ge_u32 s6, 0x300
	s_cselect_b32 s7, 0x300, 0
	s_cselect_b32 s35, 0x100, 0
	s_sub_i32 s7, s6, s7
	s_lshl_b32 s7, s7, 5
	s_add_i32 s7, s7, s35
	s_and_b32 s50, s5, 1
	s_lshr_b32 s51, s5, 1
	s_lshl_b32 s52, s51, 7
	s_add_i32 s52, s52, 0x7e
	s_add_i32 s52, s52, s50
	s_lshl_b32 s53, s51, 3
	s_add_i32 s53, s53, s50
	s_sub_i32 s53, s53, 26
	s_cmp_lt_u32 s51, 4
	s_cselect_b32 s52, s52, s53
	s_cselect_b32 s54, s18, s20
	s_cselect_b32 s55, s19, s21
	s_mov_b32 s53, 0x53dc000
	s_cselect_b32 s53, 0x485c000, s53
	s_mul_i32 s52, s52, 0x6000
	s_add_i32 s52, s52, s7
	s_add_u32 s54, s54, s52
	s_addc_u32 s55, s55, 0
	global_load_dwordx4 v[12:15], v1, s[54:55]
	s_mul_i32 s52, s5, 0xc000
	s_add_u32 s52, s52, s53
	s_lshl_b32 s6, s6, 5
	s_add_u32 s52, s52, s6
	s_add_u32 s58, s16, s52
	s_addc_u32 s59, s17, 0
	s_add_i32 s4, s0, 0x40000
	s_lshr_b32 s5, s4, 9
	s_mul_i32 s5, s5, 0xaaab
	s_lshr_b32 s5, s5, 17
	s_mul_i32 s6, s5, 0x600
	s_sub_i32 s6, s4, s6
	s_cmp_ge_u32 s6, 0x300
	s_cselect_b32 s7, 0x300, 0
	s_cselect_b32 s35, 0x100, 0
	s_sub_i32 s7, s6, s7
	s_lshl_b32 s7, s7, 5
	s_add_i32 s7, s7, s35
	s_and_b32 s50, s5, 1
	s_lshr_b32 s51, s5, 1
	s_lshl_b32 s52, s51, 7
	s_add_i32 s52, s52, 0x7e
	s_add_i32 s52, s52, s50
	s_lshl_b32 s53, s51, 3
	s_add_i32 s53, s53, s50
	s_sub_i32 s53, s53, 26
	s_cmp_lt_u32 s51, 4
	s_cselect_b32 s52, s52, s53
	s_cselect_b32 s54, s18, s20
	s_cselect_b32 s55, s19, s21
	s_mov_b32 s53, 0x53dc000
	s_cselect_b32 s53, 0x485c000, s53
	s_mul_i32 s52, s52, 0x6000
	s_add_i32 s52, s52, s7
	s_add_u32 s54, s54, s52
	s_addc_u32 s55, s55, 0
	global_load_dwordx4 v[16:19], v1, s[54:55]
	s_mul_i32 s52, s5, 0xc000
	s_add_u32 s52, s52, s53
	s_lshl_b32 s6, s6, 5
	s_add_u32 s52, s52, s6
	s_add_u32 s60, s16, s52
	s_addc_u32 s61, s17, 0
	s_add_i32 s4, s0, 0x60000
	s_cmp_eq_u32 s64, 1
	s_cselect_b32 s4, s4, s0
	s_lshr_b32 s5, s4, 9
	s_mul_i32 s5, s5, 0xaaab
	s_lshr_b32 s5, s5, 17
	s_mul_i32 s6, s5, 0x600
	s_sub_i32 s6, s4, s6
	s_cmp_ge_u32 s6, 0x300
	s_cselect_b32 s7, 0x300, 0
	s_cselect_b32 s35, 0x100, 0
	s_sub_i32 s7, s6, s7
	s_lshl_b32 s7, s7, 5
	s_add_i32 s7, s7, s35
	s_and_b32 s50, s5, 1
	s_lshr_b32 s51, s5, 1
	s_lshl_b32 s52, s51, 7
	s_add_i32 s52, s52, 0x7e
	s_add_i32 s52, s52, s50
	s_lshl_b32 s53, s51, 3
	s_add_i32 s53, s53, s50
	s_sub_i32 s53, s53, 26
	s_cmp_lt_u32 s51, 4
	s_cselect_b32 s52, s52, s53
	s_cselect_b32 s54, s18, s20
	s_cselect_b32 s55, s19, s21
	s_mov_b32 s53, 0x53dc000
	s_cselect_b32 s53, 0x485c000, s53
	s_mul_i32 s52, s52, 0x6000
	s_add_i32 s52, s52, s7
	s_add_u32 s54, s54, s52
	s_addc_u32 s55, s55, 0
	global_load_dwordx4 v[20:23], v1, s[54:55]
	s_mul_i32 s52, s5, 0xc000
	s_add_u32 s52, s52, s53
	s_lshl_b32 s6, s6, 5
	s_add_u32 s52, s52, s6
	s_add_u32 s62, s16, s52
	s_addc_u32 s63, s17, 0
	s_cmp_lt_u32 s0, 0x10000
	s_cselect_b32 s65, 1, 0
	s_mov_b32 s4, s0
	s_lshr_b32 s5, s4, 8
	s_mul_i32 s5, s5, 0xaaab
	s_lshr_b32 s5, s5, 17
	s_mul_i32 s6, s5, 0x300
	s_sub_i32 s6, s4, s6
	s_lshl_b32 s35, s6, 5
	s_add_u32 s48, s10, s35
	s_addc_u32 s49, s11, 0
	global_load_dwordx4 v[24:27], v2, s[48:49]
	global_load_dwordx4 v[28:31], v2, s[48:49] offset:16
	s_add_u32 s48, s48, 0x6000
	s_addc_u32 s49, s49, 0
	global_load_dwordx4 v[32:35], v2, s[48:49]
	global_load_dwordx4 v[36:39], v2, s[48:49] offset:16
	s_add_u32 s48, s48, 0x6000
	s_addc_u32 s49, s49, 0
	global_load_dwordx4 v[40:43], v2, s[48:49]
	global_load_dwordx4 v[44:47], v2, s[48:49] offset:16
	s_add_u32 s48, s48, 0x6000
	s_addc_u32 s49, s49, 0
	global_load_dwordx4 v[48:51], v2, s[48:49]
	global_load_dwordx4 v[52:55], v2, s[48:49] offset:16
	s_add_u32 s48, s48, 0x6000
	s_addc_u32 s49, s49, 0
; __device__ __forceinline__ void phase_ffnconv(const Params& p) {
;     ...
;     for (int it = gt; it < 128 * 2 * NCH; it += NGT) {
;         const int c = it % NCH, q = it / NCH, sl = q & 1, blk = q >> 1, j0 = 8 * c, colg = (j0 >> 7) * 256 + (j0 & 127);
;         const int row = blk * 64 + sl; const bool first = (blk & 31) == 0;
;         float wg[3][8], wv[3][8], ag[8], av[8];
; #pragma unroll
;         for (int k = 0; k < 3; ++k) { ld8f(p.in[I_WFCONV] + (size_t)k * 2 * DFF + j0, wg[k]); ld8f(p.in[I_WFCONV] + (size_t)k * 2 * DFF + DFF + j0, wv[k]); }
;         ld8f(p.in[I_BFCONV] + j0, ag); ld8f(p.in[I_BFCONV] + DFF + j0, av);
; #pragma unroll
;         for (int k = 0; k < 3; ++k) { const int d = k - 2 + sl;
;             if (d < 0 && first) continue;
;             const size_t ub = d < 0 ? (size_t)((blk - 1) * 4 + 4 + d) : (size_t)(blk * 4 + d);
;             float xg[8], xv[8]; unpack8(*(const u32x4*)(UPB + ub * (2 * DFF) + colg), xg); unpack8(*(const u32x4*)(UPB + ub * (2 * DFF) + colg + 128), xv);
;     ...
;     for (int i = gt; i < NSEQ * 2 * (2 * DFF / 8); i += NGT) { const int c = i % 1536, q = i / 1536, r = q & 1, s = q >> 1, n0 = 8 * c;
;         const int j0 = n0 < DFF ? n0 : n0 - DFF, col = (j0 >> 7) * 256 + (n0 < DFF ? 0 : 128) + (j0 & 127);
;         const int row = s < 4 ? s * SEQ + SEQ - 2 + r : MPROMPT + (s - 4) * 8 + 6 + r;
;         float x[8];
;         if (s < 4) unpack8(*(const u32x4*)(UPB + ((size_t)(s * 32 + 31) * 4 + 2 + r) * (2 * DFF) + col), x); else unpack8(*(const u32x4*)(UP + (size_t)row * 2 * DFF + col), x);
;         float* o = p.out + (s < 4 ? O_FCONVP + ((size_t)s * 2 + r) * 2 * DFF : O_FCONVS + ((size_t)(s - 4) * 2 + r) * 2 * DFF) + n0;
;         __builtin_nontemporal_store((f32x4){x[0], x[1], x[2], x[3]}, (f32x4*)o); __builtin_nontemporal_store((f32x4){x[4], x[5], x[6], x[7]}, (f32x4*)(o + 4)); }
	global_load_dwordx4 v[56:59], v2, s[48:49]
	global_load_dwordx4 v[60:63], v2, s[48:49] offset:16
	s_add_u32 s48, s48, 0x6000
	s_addc_u32 s49, s49, 0
	global_load_dwordx4 v[64:67], v2, s[48:49]
	global_load_dwordx4 v[68:71], v2, s[48:49] offset:16
	s_add_u32 s48, s12, s35
	s_addc_u32 s49, s13, 0
	global_load_dwordx4 v[72:75], v2, s[48:49]
	global_load_dwordx4 v[76:79], v2, s[48:49] offset:16
	s_add_u32 s48, s48, 0x6000
	s_addc_u32 s49, s49, 0
	global_load_dwordx4 v[80:83], v2, s[48:49]
	global_load_dwordx4 v[84:87], v2, s[48:49] offset:16
	s_and_b32 s50, s5, 1
	s_lshr_b32 s51, s5, 1
	s_and_b32 s52, s51, 31
	s_cmp_eq_u32 s52, 0
	s_cselect_b32 s52, 1, 0
	s_xor_b32 s53, s50, 1
	s_and_b32 s53, s53, s52
	s_lshl_b32 s53, s53, 1
	s_or_b32 s38, s53, s52
	s_lshl_b32 s7, s6, 5
	s_lshl_b32 s53, s51, 2
	s_add_i32 s53, s53, s50
	s_add_i32 s53, s53, -2
	s_max_i32 s53, s53, 0
	s_mul_i32 s53, s53, 0x6000
	s_add_i32 s53, s53, s7
	s_add_u32 s54, s18, s53
	s_addc_u32 s55, s19, 0
	global_load_dwordx4 v[88:91], v1, s[54:55]
	global_load_dwordx4 v[92:95], v1, s[54:55] offset:256
	s_lshl_b32 s53, s51, 2
	s_add_i32 s53, s53, s50
	s_add_i32 s53, s53, -1
	s_max_i32 s53, s53, 0
	s_mul_i32 s53, s53, 0x6000
	s_add_i32 s53, s53, s7
	s_add_u32 s54, s18, s53
	s_addc_u32 s55, s19, 0
	global_load_dwordx4 v[96:99], v1, s[54:55]
	global_load_dwordx4 v[100:103], v1, s[54:55] offset:256
	s_lshl_b32 s53, s51, 2
	s_add_i32 s53, s53, s50
	s_add_i32 s53, s53, 0
	s_max_i32 s53, s53, 0
	s_mul_i32 s53, s53, 0x6000
	s_add_i32 s53, s53, s7
	s_add_u32 s54, s18, s53
	s_addc_u32 s55, s19, 0
	global_load_dwordx4 v[104:107], v1, s[54:55]
	global_load_dwordx4 v[108:111], v1, s[54:55] offset:256
	s_lshl_b32 s53, s51, 6
	s_add_i32 s53, s53, s50
	s_mul_i32 s53, s53, 0x3000
	s_lshl_b32 s52, s6, 4
	s_add_i32 s53, s53, s52
	s_add_u32 s30, s22, s53
	s_addc_u32 s31, s23, 0
	s_add_i32 s4, s0, 0x20000
	s_cmp_eq_u32 s65, 1
	s_cselect_b32 s4, s4, s0
	s_lshr_b32 s5, s4, 8
	s_mul_i32 s5, s5, 0xaaab
	s_lshr_b32 s5, s5, 17
	s_mul_i32 s6, s5, 0x300
	s_sub_i32 s6, s4, s6
	s_lshl_b32 s35, s6, 5
	s_add_u32 s48, s10, s35
	s_addc_u32 s49, s11, 0
	global_load_dwordx4 v[112:115], v2, s[48:49]
	global_load_dwordx4 v[116:119], v2, s[48:49] offset:16
	s_add_u32 s48, s48, 0x6000
	s_addc_u32 s49, s49, 0
	global_load_dwordx4 v[120:123], v2, s[48:49]
	global_load_dwordx4 v[124:127], v2, s[48:49] offset:16
	s_add_u32 s48, s48, 0x6000
	s_addc_u32 s49, s49, 0
	global_load_dwordx4 v[128:131], v2, s[48:49]
	global_load_dwordx4 v[132:135], v2, s[48:49] offset:16
	s_add_u32 s48, s48, 0x6000
	s_addc_u32 s49, s49, 0
	global_load_dwordx4 v[136:139], v2, s[48:49]
	global_load_dwordx4 v[140:143], v2, s[48:49] offset:16
	s_add_u32 s48, s48, 0x6000
	s_addc_u32 s49, s49, 0
	global_load_dwordx4 v[144:147], v2, s[48:49]
	global_load_dwordx4 v[148:151], v2, s[48:49] offset:16
	s_add_u32 s48, s48, 0x6000
	s_addc_u32 s49, s49, 0
	global_load_dwordx4 v[152:155], v2, s[48:49]
	global_load_dwordx4 v[156:159], v2, s[48:49] offset:16
	s_add_u32 s48, s12, s35
	s_addc_u32 s49, s13, 0
	global_load_dwordx4 v[160:163], v2, s[48:49]
	global_load_dwordx4 v[164:167], v2, s[48:49] offset:16
	s_add_u32 s48, s48, 0x6000
	s_addc_u32 s49, s49, 0
	global_load_dwordx4 v[168:171], v2, s[48:49]
	global_load_dwordx4 v[172:175], v2, s[48:49] offset:16
	s_and_b32 s50, s5, 1
	s_lshr_b32 s51, s5, 1
	s_and_b32 s52, s51, 31
	s_cmp_eq_u32 s52, 0
	s_cselect_b32 s52, 1, 0
	s_xor_b32 s53, s50, 1
	s_and_b32 s53, s53, s52
	s_lshl_b32 s53, s53, 1
	s_or_b32 s39, s53, s52
	s_lshl_b32 s7, s6, 5
	s_lshl_b32 s53, s51, 2
	s_add_i32 s53, s53, s50
	s_add_i32 s53, s53, -2
	s_max_i32 s53, s53, 0
	s_mul_i32 s53, s53, 0x6000
	s_add_i32 s53, s53, s7
	s_add_u32 s54, s18, s53
	s_addc_u32 s55, s19, 0
	global_load_dwordx4 v[176:179], v1, s[54:55]
	global_load_dwordx4 v[180:183], v1, s[54:55] offset:256
	s_lshl_b32 s53, s51, 2
	s_add_i32 s53, s53, s50
	s_add_i32 s53, s53, -1
	s_max_i32 s53, s53, 0
	s_mul_i32 s53, s53, 0x6000
	s_add_i32 s53, s53, s7
	s_add_u32 s54, s18, s53
	s_addc_u32 s55, s19, 0
	global_load_dwordx4 v[184:187], v1, s[54:55]
	global_load_dwordx4 v[188:191], v1, s[54:55] offset:256
	s_lshl_b32 s53, s51, 2
	s_add_i32 s53, s53, s50
	s_add_i32 s53, s53, 0
	s_max_i32 s53, s53, 0
	s_mul_i32 s53, s53, 0x6000
	s_add_i32 s53, s53, s7
	s_add_u32 s54, s18, s53
	s_addc_u32 s55, s19, 0
	global_load_dwordx4 v[192:195], v1, s[54:55]
	global_load_dwordx4 v[196:199], v1, s[54:55] offset:256
	s_lshl_b32 s53, s51, 6
	s_add_i32 s53, s53, s50
	s_mul_i32 s53, s53, 0x3000
	s_lshl_b32 s52, s6, 4
	s_add_i32 s53, s53, s52
	s_add_u32 s36, s22, s53
	s_addc_u32 s37, s23, 0
	s_waitcnt vmcnt(44)
	v_lshlrev_b32_e32 v200, 16, v8
	v_and_b32_e32 v201, 0xffff0000, v8
	v_lshlrev_b32_e32 v202, 16, v9
	v_and_b32_e32 v203, 0xffff0000, v9
	v_lshlrev_b32_e32 v204, 16, v10
	v_and_b32_e32 v205, 0xffff0000, v10
	v_lshlrev_b32_e32 v206, 16, v11
	v_and_b32_e32 v207, 0xffff0000, v11
	global_store_dwordx4 v2, v[200:203], s[56:57] nt
	global_store_dwordx4 v2, v[204:207], s[56:57] offset:16 nt
	s_nop 1
	v_lshlrev_b32_e32 v200, 16, v12
	v_and_b32_e32 v201, 0xffff0000, v12
	v_lshlrev_b32_e32 v202, 16, v13
	v_and_b32_e32 v203, 0xffff0000, v13
	v_lshlrev_b32_e32 v204, 16, v14
	v_and_b32_e32 v205, 0xffff0000, v14
	v_lshlrev_b32_e32 v206, 16, v15
	v_and_b32_e32 v207, 0xffff0000, v15
	global_store_dwordx4 v2, v[200:203], s[58:59] nt
	global_store_dwordx4 v2, v[204:207], s[58:59] offset:16 nt
	s_nop 1
	v_lshlrev_b32_e32 v200, 16, v16
	v_and_b32_e32 v201, 0xffff0000, v16
	v_lshlrev_b32_e32 v202, 16, v17
	v_and_b32_e32 v203, 0xffff0000, v17
	v_lshlrev_b32_e32 v204, 16, v18
	v_and_b32_e32 v205, 0xffff0000, v18
	v_lshlrev_b32_e32 v206, 16, v19
	v_and_b32_e32 v207, 0xffff0000, v19
	global_store_dwordx4 v2, v[200:203], s[60:61] nt
	global_store_dwordx4 v2, v[204:207], s[60:61] offset:16 nt
	s_nop 1
	s_cmp_eq_u32 s64, 1
	s_cbranch_scc0 .Lp11_s3done
	v_lshlrev_b32_e32 v200, 16, v20
	v_and_b32_e32 v201, 0xffff0000, v20
	v_lshlrev_b32_e32 v202, 16, v21
	v_and_b32_e32 v203, 0xffff0000, v21
	v_lshlrev_b32_e32 v204, 16, v22
	v_and_b32_e32 v205, 0xffff0000, v22
	v_lshlrev_b32_e32 v206, 16, v23
	v_and_b32_e32 v207, 0xffff0000, v23
	global_store_dwordx4 v2, v[200:203], s[62:63] nt
	global_store_dwordx4 v2, v[204:207], s[62:63] offset:16 nt
	s_nop 1
; __device__ __forceinline__ u32x4 pack8(const float (&f)[8]) { u32x4 w; w.x = pk2(f[0], f[1]); w.y = pk2(f[2], f[3]); w.z = pk2(f[4], f[5]); w.w = pk2(f[6], f[7]); return w; }
; __device__ __forceinline__ float gelu_tanh(float x) { const float y = 1.5957691216f * (x + 0.044715f * x * x * x); return x * __builtin_amdgcn_rcpf(1.0f + __expf(-y)); }
; __device__ __forceinline__ void phase_ffnconv(const Params& p) {
;     ...
;         for (int k = 0; k < 3; ++k) { const int d = k - 2 + sl;
;             if (d < 0 && first) continue;
;             const size_t ub = d < 0 ? (size_t)((blk - 1) * 4 + 4 + d) : (size_t)(blk * 4 + d);
;             float xg[8], xv[8]; unpack8(*(const u32x4*)(UPB + ub * (2 * DFF) + colg), xg); unpack8(*(const u32x4*)(UPB + ub * (2 * DFF) + colg + 128), xv);
; #pragma unroll
;             for (int e = 0; e < 8; ++e) { ag[e] += xg[e] * wg[k][e]; av[e] += xv[e] * wv[k][e]; } }
;         float f[8];
; #pragma unroll
;         for (int e = 0; e < 8; ++e) f[e] = gelu_tanh(ag[e]) * av[e];
;         *(u32x4*)(F + (size_t)row * DFF + j0) = pack8(f);
.Lp11_s3done:
	s_waitcnt vmcnt(28)
	s_bitcmp1_b32 s38, 0
	s_cbranch_scc0 .Lp11_s1z00
	v_mov_b32_e32 v88, 0
	v_mov_b32_e32 v89, 0
	v_mov_b32_e32 v90, 0
	v_mov_b32_e32 v91, 0
	v_mov_b32_e32 v92, 0
	v_mov_b32_e32 v93, 0
	v_mov_b32_e32 v94, 0
	v_mov_b32_e32 v95, 0
.Lp11_s1z00:
	s_bitcmp1_b32 s38, 1
	s_cbranch_scc0 .Lp11_s1z01
	v_mov_b32_e32 v96, 0
	v_mov_b32_e32 v97, 0
	v_mov_b32_e32 v98, 0
	v_mov_b32_e32 v99, 0
	v_mov_b32_e32 v100, 0
	v_mov_b32_e32 v101, 0
	v_mov_b32_e32 v102, 0
	v_mov_b32_e32 v103, 0
.Lp11_s1z01:
	v_lshlrev_b32_e32 v200, 16, v88
	v_and_b32_e32 v201, 0xffff0000, v88
	v_lshlrev_b32_e32 v202, 16, v89
	v_and_b32_e32 v203, 0xffff0000, v89
	v_lshlrev_b32_e32 v204, 16, v90
	v_and_b32_e32 v205, 0xffff0000, v90
	v_lshlrev_b32_e32 v206, 16, v91
	v_and_b32_e32 v207, 0xffff0000, v91
	v_lshlrev_b32_e32 v234, 16, v92
	v_and_b32_e32 v235, 0xffff0000, v92
	v_lshlrev_b32_e32 v236, 16, v93
	v_and_b32_e32 v237, 0xffff0000, v93
	v_lshlrev_b32_e32 v238, 16, v94
	v_and_b32_e32 v239, 0xffff0000, v94
	v_lshlrev_b32_e32 v240, 16, v95
	v_and_b32_e32 v241, 0xffff0000, v95
	v_lshlrev_b32_e32 v8, 16, v96
	v_and_b32_e32 v9, 0xffff0000, v96
	v_lshlrev_b32_e32 v10, 16, v97
	v_and_b32_e32 v11, 0xffff0000, v97
	v_lshlrev_b32_e32 v12, 16, v98
	v_and_b32_e32 v13, 0xffff0000, v98
	v_lshlrev_b32_e32 v14, 16, v99
	v_and_b32_e32 v15, 0xffff0000, v99
	v_lshlrev_b32_e32 v16, 16, v100
	v_and_b32_e32 v17, 0xffff0000, v100
	v_lshlrev_b32_e32 v18, 16, v101
	v_and_b32_e32 v19, 0xffff0000, v101
	v_lshlrev_b32_e32 v20, 16, v102
	v_and_b32_e32 v21, 0xffff0000, v102
	v_lshlrev_b32_e32 v22, 16, v103
	v_and_b32_e32 v23, 0xffff0000, v103
	v_lshlrev_b32_e32 v88, 16, v104
	v_and_b32_e32 v89, 0xffff0000, v104
	v_lshlrev_b32_e32 v90, 16, v105
	v_and_b32_e32 v91, 0xffff0000, v105
	v_lshlrev_b32_e32 v92, 16, v106
	v_and_b32_e32 v93, 0xffff0000, v106
	v_lshlrev_b32_e32 v94, 16, v107
	v_and_b32_e32 v95, 0xffff0000, v107
	v_lshlrev_b32_e32 v96, 16, v108
	v_and_b32_e32 v97, 0xffff0000, v108
	v_lshlrev_b32_e32 v98, 16, v109
	v_and_b32_e32 v99, 0xffff0000, v109
	v_lshlrev_b32_e32 v100, 16, v110
	v_and_b32_e32 v101, 0xffff0000, v110
	v_lshlrev_b32_e32 v102, 16, v111
	v_and_b32_e32 v103, 0xffff0000, v111
	v_pk_fma_f32 v[242:243], v[200:201], v[24:25], v[72:73]
	v_pk_fma_f32 v[224:225], v[234:235], v[32:33], v[80:81]
	v_pk_fma_f32 v[244:245], v[202:203], v[26:27], v[74:75]
	v_pk_fma_f32 v[226:227], v[236:237], v[34:35], v[82:83]
	v_pk_fma_f32 v[246:247], v[204:205], v[28:29], v[76:77]
	v_pk_fma_f32 v[228:229], v[238:239], v[36:37], v[84:85]
	v_pk_fma_f32 v[248:249], v[206:207], v[30:31], v[78:79]
	v_pk_fma_f32 v[230:231], v[240:241], v[38:39], v[86:87]
	v_pk_fma_f32 v[242:243], v[8:9], v[40:41], v[242:243]
	v_pk_fma_f32 v[224:225], v[16:17], v[48:49], v[224:225]
	v_pk_fma_f32 v[244:245], v[10:11], v[42:43], v[244:245]
	v_pk_fma_f32 v[226:227], v[18:19], v[50:51], v[226:227]
	v_pk_fma_f32 v[246:247], v[12:13], v[44:45], v[246:247]
	v_pk_fma_f32 v[228:229], v[20:21], v[52:53], v[228:229]
	v_pk_fma_f32 v[248:249], v[14:15], v[46:47], v[248:249]
	v_pk_fma_f32 v[230:231], v[22:23], v[54:55], v[230:231]
	v_pk_fma_f32 v[242:243], v[88:89], v[56:57], v[242:243]
	v_pk_fma_f32 v[224:225], v[96:97], v[64:65], v[224:225]
	v_pk_fma_f32 v[244:245], v[90:91], v[58:59], v[244:245]
	v_pk_fma_f32 v[226:227], v[98:99], v[66:67], v[226:227]
	v_pk_fma_f32 v[246:247], v[92:93], v[60:61], v[246:247]
	v_pk_fma_f32 v[228:229], v[100:101], v[68:69], v[228:229]
	v_pk_fma_f32 v[248:249], v[94:95], v[62:63], v[248:249]
	v_pk_fma_f32 v[230:231], v[102:103], v[70:71], v[230:231]
	v_pk_mul_f32 v[200:201], v[242:243], v[242:243]
	v_pk_mul_f32 v[202:203], v[244:245], v[244:245]
	v_pk_mul_f32 v[204:205], v[246:247], v[246:247]
	v_pk_mul_f32 v[206:207], v[248:249], v[248:249]
	v_pk_fma_f32 v[200:201], v[200:201], s[26:27], v[4:5]
	v_pk_fma_f32 v[202:203], v[202:203], s[26:27], v[4:5]
	v_pk_fma_f32 v[204:205], v[204:205], s[26:27], v[4:5]
	v_pk_fma_f32 v[206:207], v[206:207], s[26:27], v[4:5]
	v_pk_mul_f32 v[200:201], v[242:243], v[200:201]
	v_pk_mul_f32 v[202:203], v[244:245], v[202:203]
	v_pk_mul_f32 v[204:205], v[246:247], v[204:205]
	v_pk_mul_f32 v[206:207], v[248:249], v[206:207]
	v_exp_f32_e32 v200, v200
	v_exp_f32_e32 v201, v201
	v_exp_f32_e32 v202, v202
	v_exp_f32_e32 v203, v203
	v_exp_f32_e32 v204, v204
	v_exp_f32_e32 v205, v205
	v_exp_f32_e32 v206, v206
	v_exp_f32_e32 v207, v207
	v_pk_add_f32 v[200:201], v[200:201], s[28:29]
	v_pk_add_f32 v[202:203], v[202:203], s[28:29]
	v_pk_add_f32 v[204:205], v[204:205], s[28:29]
	v_pk_add_f32 v[206:207], v[206:207], s[28:29]
	v_rcp_f32_e32 v200, v200
	v_rcp_f32_e32 v201, v201
	v_rcp_f32_e32 v202, v202
	v_rcp_f32_e32 v203, v203
	v_rcp_f32_e32 v204, v204
	v_rcp_f32_e32 v205, v205
	v_rcp_f32_e32 v206, v206
	v_rcp_f32_e32 v207, v207
	v_pk_mul_f32 v[200:201], v[242:243], v[200:201]
	v_pk_mul_f32 v[202:203], v[244:245], v[202:203]
	v_pk_mul_f32 v[204:205], v[246:247], v[204:205]
	v_pk_mul_f32 v[206:207], v[248:249], v[206:207]
	v_pk_mul_f32 v[200:201], v[200:201], v[224:225]
	v_pk_mul_f32 v[202:203], v[202:203], v[226:227]
	v_pk_mul_f32 v[204:205], v[204:205], v[228:229]
	v_pk_mul_f32 v[206:207], v[206:207], v[230:231]
	v_cvt_pk_bf16_f32 v250, v200, v201
	v_cvt_pk_bf16_f32 v251, v202, v203
	v_cvt_pk_bf16_f32 v252, v204, v205
	v_cvt_pk_bf16_f32 v253, v206, v207
	global_store_dwordx4 v3, v[250:253], s[30:31]
	s_waitcnt vmcnt(7)
	s_cmp_eq_u32 s65, 1
	s_cbranch_scc0 .Lp11_s1done
	s_bitcmp1_b32 s39, 0
	s_cbranch_scc0 .Lp11_s1z10
	v_mov_b32_e32 v176, 0
	v_mov_b32_e32 v177, 0
	v_mov_b32_e32 v178, 0
	v_mov_b32_e32 v179, 0
	v_mov_b32_e32 v180, 0
	v_mov_b32_e32 v181, 0
	v_mov_b32_e32 v182, 0
	v_mov_b32_e32 v183, 0
; __device__ __forceinline__ u32x4 pack8(const float (&f)[8]) { u32x4 w; w.x = pk2(f[0], f[1]); w.y = pk2(f[2], f[3]); w.z = pk2(f[4], f[5]); w.w = pk2(f[6], f[7]); return w; }
; __device__ __forceinline__ float gelu_tanh(float x) { const float y = 1.5957691216f * (x + 0.044715f * x * x * x); return x * __builtin_amdgcn_rcpf(1.0f + __expf(-y)); }
; __device__ __forceinline__ void phase_ffnconv(const Params& p) {
;     ...
;         for (int k = 0; k < 3; ++k) { const int d = k - 2 + sl;
;             if (d < 0 && first) continue;
;             const size_t ub = d < 0 ? (size_t)((blk - 1) * 4 + 4 + d) : (size_t)(blk * 4 + d);
;             float xg[8], xv[8]; unpack8(*(const u32x4*)(UPB + ub * (2 * DFF) + colg), xg); unpack8(*(const u32x4*)(UPB + ub * (2 * DFF) + colg + 128), xv);
; #pragma unroll
;             for (int e = 0; e < 8; ++e) { ag[e] += xg[e] * wg[k][e]; av[e] += xv[e] * wv[k][e]; } }
;         float f[8];
; #pragma unroll
;         for (int e = 0; e < 8; ++e) f[e] = gelu_tanh(ag[e]) * av[e];
;         *(u32x4*)(F + (size_t)row * DFF + j0) = pack8(f);
.Lp11_s1z10:
	s_bitcmp1_b32 s39, 1
	s_cbranch_scc0 .Lp11_s1z11
	v_mov_b32_e32 v184, 0
	v_mov_b32_e32 v185, 0
	v_mov_b32_e32 v186, 0
	v_mov_b32_e32 v187, 0
	v_mov_b32_e32 v188, 0
	v_mov_b32_e32 v189, 0
	v_mov_b32_e32 v190, 0
	v_mov_b32_e32 v191, 0
.Lp11_s1z11:
	v_lshlrev_b32_e32 v200, 16, v176
	v_and_b32_e32 v201, 0xffff0000, v176
	v_lshlrev_b32_e32 v202, 16, v177
	v_and_b32_e32 v203, 0xffff0000, v177
	v_lshlrev_b32_e32 v204, 16, v178
	v_and_b32_e32 v205, 0xffff0000, v178
	v_lshlrev_b32_e32 v206, 16, v179
	v_and_b32_e32 v207, 0xffff0000, v179
	v_lshlrev_b32_e32 v234, 16, v180
	v_and_b32_e32 v235, 0xffff0000, v180
	v_lshlrev_b32_e32 v236, 16, v181
	v_and_b32_e32 v237, 0xffff0000, v181
	v_lshlrev_b32_e32 v238, 16, v182
	v_and_b32_e32 v239, 0xffff0000, v182
	v_lshlrev_b32_e32 v240, 16, v183
	v_and_b32_e32 v241, 0xffff0000, v183
	v_lshlrev_b32_e32 v8, 16, v184
	v_and_b32_e32 v9, 0xffff0000, v184
	v_lshlrev_b32_e32 v10, 16, v185
	v_and_b32_e32 v11, 0xffff0000, v185
	v_lshlrev_b32_e32 v12, 16, v186
	v_and_b32_e32 v13, 0xffff0000, v186
	v_lshlrev_b32_e32 v14, 16, v187
	v_and_b32_e32 v15, 0xffff0000, v187
	v_lshlrev_b32_e32 v16, 16, v188
	v_and_b32_e32 v17, 0xffff0000, v188
	v_lshlrev_b32_e32 v18, 16, v189
	v_and_b32_e32 v19, 0xffff0000, v189
	v_lshlrev_b32_e32 v20, 16, v190
	v_and_b32_e32 v21, 0xffff0000, v190
	v_lshlrev_b32_e32 v22, 16, v191
	v_and_b32_e32 v23, 0xffff0000, v191
	v_lshlrev_b32_e32 v176, 16, v192
	v_and_b32_e32 v177, 0xffff0000, v192
	v_lshlrev_b32_e32 v178, 16, v193
	v_and_b32_e32 v179, 0xffff0000, v193
	v_lshlrev_b32_e32 v180, 16, v194
	v_and_b32_e32 v181, 0xffff0000, v194
	v_lshlrev_b32_e32 v182, 16, v195
	v_and_b32_e32 v183, 0xffff0000, v195
	v_lshlrev_b32_e32 v184, 16, v196
	v_and_b32_e32 v185, 0xffff0000, v196
	v_lshlrev_b32_e32 v186, 16, v197
	v_and_b32_e32 v187, 0xffff0000, v197
	v_lshlrev_b32_e32 v188, 16, v198
	v_and_b32_e32 v189, 0xffff0000, v198
	v_lshlrev_b32_e32 v190, 16, v199
	v_and_b32_e32 v191, 0xffff0000, v199
	v_pk_fma_f32 v[242:243], v[200:201], v[112:113], v[160:161]
	v_pk_fma_f32 v[224:225], v[234:235], v[120:121], v[168:169]
	v_pk_fma_f32 v[244:245], v[202:203], v[114:115], v[162:163]
	v_pk_fma_f32 v[226:227], v[236:237], v[122:123], v[170:171]
	v_pk_fma_f32 v[246:247], v[204:205], v[116:117], v[164:165]
	v_pk_fma_f32 v[228:229], v[238:239], v[124:125], v[172:173]
	v_pk_fma_f32 v[248:249], v[206:207], v[118:119], v[166:167]
	v_pk_fma_f32 v[230:231], v[240:241], v[126:127], v[174:175]
	v_pk_fma_f32 v[242:243], v[8:9], v[128:129], v[242:243]
	v_pk_fma_f32 v[224:225], v[16:17], v[136:137], v[224:225]
	v_pk_fma_f32 v[244:245], v[10:11], v[130:131], v[244:245]
	v_pk_fma_f32 v[226:227], v[18:19], v[138:139], v[226:227]
	v_pk_fma_f32 v[246:247], v[12:13], v[132:133], v[246:247]
	v_pk_fma_f32 v[228:229], v[20:21], v[140:141], v[228:229]
	v_pk_fma_f32 v[248:249], v[14:15], v[134:135], v[248:249]
	v_pk_fma_f32 v[230:231], v[22:23], v[142:143], v[230:231]
	v_pk_fma_f32 v[242:243], v[176:177], v[144:145], v[242:243]
	v_pk_fma_f32 v[224:225], v[184:185], v[152:153], v[224:225]
	v_pk_fma_f32 v[244:245], v[178:179], v[146:147], v[244:245]
	v_pk_fma_f32 v[226:227], v[186:187], v[154:155], v[226:227]
	v_pk_fma_f32 v[246:247], v[180:181], v[148:149], v[246:247]
	v_pk_fma_f32 v[228:229], v[188:189], v[156:157], v[228:229]
	v_pk_fma_f32 v[248:249], v[182:183], v[150:151], v[248:249]
	v_pk_fma_f32 v[230:231], v[190:191], v[158:159], v[230:231]
	v_pk_mul_f32 v[200:201], v[242:243], v[242:243]
	v_pk_mul_f32 v[202:203], v[244:245], v[244:245]
	v_pk_mul_f32 v[204:205], v[246:247], v[246:247]
	v_pk_mul_f32 v[206:207], v[248:249], v[248:249]
	v_pk_fma_f32 v[200:201], v[200:201], s[26:27], v[4:5]
	v_pk_fma_f32 v[202:203], v[202:203], s[26:27], v[4:5]
	v_pk_fma_f32 v[204:205], v[204:205], s[26:27], v[4:5]
	v_pk_fma_f32 v[206:207], v[206:207], s[26:27], v[4:5]
	v_pk_mul_f32 v[200:201], v[242:243], v[200:201]
	v_pk_mul_f32 v[202:203], v[244:245], v[202:203]
	v_pk_mul_f32 v[204:205], v[246:247], v[204:205]
	v_pk_mul_f32 v[206:207], v[248:249], v[206:207]
	v_exp_f32_e32 v200, v200
	v_exp_f32_e32 v201, v201
	v_exp_f32_e32 v202, v202
	v_exp_f32_e32 v203, v203
	v_exp_f32_e32 v204, v204
	v_exp_f32_e32 v205, v205
	v_exp_f32_e32 v206, v206
	v_exp_f32_e32 v207, v207
	v_pk_add_f32 v[200:201], v[200:201], s[28:29]
	v_pk_add_f32 v[202:203], v[202:203], s[28:29]
	v_pk_add_f32 v[204:205], v[204:205], s[28:29]
	v_pk_add_f32 v[206:207], v[206:207], s[28:29]
	v_rcp_f32_e32 v200, v200
	v_rcp_f32_e32 v201, v201
	v_rcp_f32_e32 v202, v202
	v_rcp_f32_e32 v203, v203
	v_rcp_f32_e32 v204, v204
	v_rcp_f32_e32 v205, v205
	v_rcp_f32_e32 v206, v206
	v_rcp_f32_e32 v207, v207
	v_pk_mul_f32 v[200:201], v[242:243], v[200:201]
	v_pk_mul_f32 v[202:203], v[244:245], v[202:203]
	v_pk_mul_f32 v[204:205], v[246:247], v[204:205]
	v_pk_mul_f32 v[206:207], v[248:249], v[206:207]
	v_pk_mul_f32 v[200:201], v[200:201], v[224:225]
	v_pk_mul_f32 v[202:203], v[202:203], v[226:227]
	v_pk_mul_f32 v[204:205], v[204:205], v[228:229]
	v_pk_mul_f32 v[206:207], v[206:207], v[230:231]
	v_cvt_pk_bf16_f32 v250, v200, v201
	v_cvt_pk_bf16_f32 v251, v202, v203
	v_cvt_pk_bf16_f32 v252, v204, v205
	v_cvt_pk_bf16_f32 v253, v206, v207
	global_store_dwordx4 v3, v[250:253], s[36:37]
; __device__ __forceinline__ u32x4 pack8(const float (&f)[8]) { u32x4 w; w.x = pk2(f[0], f[1]); w.y = pk2(f[2], f[3]); w.z = pk2(f[4], f[5]); w.w = pk2(f[6], f[7]); return w; }
; __device__ __forceinline__ float gelu_tanh(float x) { const float y = 1.5957691216f * (x + 0.044715f * x * x * x); return x * __builtin_amdgcn_rcpf(1.0f + __expf(-y)); }
; __device__ __forceinline__ void phase_ffnconv(const Params& p) {
;     ...
;     if (gt < 170 * NCH) {
;         const int c = gt % NCH, slot = gt / NCH, j0 = 8 * c, colg = (j0 >> 7) * 256 + (j0 & 127);
;         float wg[3][8], wv[3][8], bg[8], bv[8];
; #pragma unroll
;         for (int k = 0; k < 3; ++k) { ld8f(p.in[I_WFCONV] + (size_t)k * 2 * DFF + j0, wg[k]); ld8f(p.in[I_WFCONV] + (size_t)k * 2 * DFF + DFF + j0, wv[k]); }
;         ld8f(p.in[I_BFCONV] + j0, bg); ld8f(p.in[I_BFCONV] + DFF + j0, bv);
;         for (int rs = slot; rs < 1024; rs += 170) {
;             const int row = MPROMPT + rs, t = rs & 7, b = rs >> 3;
;             float xg[3][8], xv[3][8];
; #pragma unroll
;             for (int k = 0; k < 3; ++k) { const int tt = t - 2 + k;
;                 if (tt >= 0) { unpack8(*(const u32x4*)(UP + (size_t)(row - 2 + k) * 2 * DFF + colg), xg[k]); unpack8(*(const u32x4*)(UP + (size_t)(row - 2 + k) * 2 * DFF + colg + 128), xv[k]); }
;                 else { const float* sp = p.in[I_SFCONV] + ((size_t)b * 2 + (2 + tt)) * 2 * DFF; ld8f(sp + j0, xg[k]); ld8f(sp + DFF + j0, xv[k]); } }
;             float f[8];
; #pragma unroll
;             for (int e = 0; e < 8; ++e) { const float cg_ = bg[e] + xg[0][e] * wg[0][e] + xg[1][e] * wg[1][e] + xg[2][e] * wg[2][e];
;                 const float cv_ = bv[e] + xv[0][e] * wv[0][e] + xv[1][e] * wv[1][e] + xv[2][e] * wv[2][e]; f[e] = gelu_tanh(cg_) * cv_; }
;             *(u32x4*)(F + (size_t)row * DFF + j0) = pack8(f);
.Lp11_s1done:
	s_cmp_lt_u32 s0, 0x18000
	s_cbranch_scc0 .Lp11_done
	s_lshr_b32 s5, s0, 8
	s_mul_i32 s5, s5, 0xaaab
	s_lshr_b32 s5, s5, 17
	s_mul_i32 s6, s5, 0x300
	s_sub_i32 s6, s0, s6
	s_lshl_b32 s35, s6, 5
	s_add_u32 s48, s10, s35
	s_addc_u32 s49, s11, 0
	global_load_dwordx4 v[24:27], v2, s[48:49]
	global_load_dwordx4 v[28:31], v2, s[48:49] offset:16
	s_add_u32 s48, s48, 0x6000
	s_addc_u32 s49, s49, 0
	global_load_dwordx4 v[32:35], v2, s[48:49]
	global_load_dwordx4 v[36:39], v2, s[48:49] offset:16
	s_add_u32 s48, s48, 0x6000
	s_addc_u32 s49, s49, 0
	global_load_dwordx4 v[40:43], v2, s[48:49]
	global_load_dwordx4 v[44:47], v2, s[48:49] offset:16
	s_add_u32 s48, s48, 0x6000
	s_addc_u32 s49, s49, 0
	global_load_dwordx4 v[48:51], v2, s[48:49]
	global_load_dwordx4 v[52:55], v2, s[48:49] offset:16
	s_add_u32 s48, s48, 0x6000
	s_addc_u32 s49, s49, 0
	global_load_dwordx4 v[56:59], v2, s[48:49]
	global_load_dwordx4 v[60:63], v2, s[48:49] offset:16
	s_add_u32 s48, s48, 0x6000
	s_addc_u32 s49, s49, 0
	global_load_dwordx4 v[64:67], v2, s[48:49]
	global_load_dwordx4 v[68:71], v2, s[48:49] offset:16
	s_add_u32 s48, s12, s35
	s_addc_u32 s49, s13, 0
	global_load_dwordx4 v[72:75], v2, s[48:49]
	global_load_dwordx4 v[76:79], v2, s[48:49] offset:16
	s_add_u32 s48, s48, 0x6000
	s_addc_u32 s49, s49, 0
	global_load_dwordx4 v[80:83], v2, s[48:49]
	global_load_dwordx4 v[84:87], v2, s[48:49] offset:16
	s_mul_i32 s53, s5, 0x18000
	s_lshl_b32 s52, s6, 5
	s_add_u32 s53, s53, s52
	s_add_u32 s54, s14, s53
	s_addc_u32 s55, s15, 0
	global_load_dwordx4 v[88:91], v2, s[54:55]
	global_load_dwordx4 v[92:95], v2, s[54:55] offset:16
	s_add_u32 s54, s54, 0x6000
	s_addc_u32 s55, s55, 0
	global_load_dwordx4 v[96:99], v2, s[54:55]
	global_load_dwordx4 v[100:103], v2, s[54:55] offset:16
	s_add_u32 s54, s54, 0x6000
	s_addc_u32 s55, s55, 0
	global_load_dwordx4 v[104:107], v2, s[54:55]
	global_load_dwordx4 v[108:111], v2, s[54:55] offset:16
	s_add_u32 s54, s54, 0x6000
	s_addc_u32 s55, s55, 0
	global_load_dwordx4 v[112:115], v2, s[54:55]
	global_load_dwordx4 v[116:119], v2, s[54:55] offset:16
	s_add_u32 s54, s54, 0x6000
	s_addc_u32 s55, s55, 0
	s_mul_i32 s53, s5, 0x30000
	s_add_u32 s53, s53, s52
	s_add_u32 s54, s20, s53
	s_addc_u32 s55, s21, 0
	global_load_dwordx4 v[136:139], v1, s[54:55]
	global_load_dwordx4 v[140:143], v1, s[54:55] offset:256
	s_add_u32 s54, s54, 0x6000
	s_addc_u32 s55, s55, 0
	global_load_dwordx4 v[144:147], v1, s[54:55]
	global_load_dwordx4 v[148:151], v1, s[54:55] offset:256
	s_add_u32 s54, s54, 0x6000
	s_addc_u32 s55, s55, 0
	global_load_dwordx4 v[152:155], v1, s[54:55]
	global_load_dwordx4 v[156:159], v1, s[54:55] offset:256
	s_add_u32 s54, s54, 0x6000
	s_addc_u32 s55, s55, 0
	global_load_dwordx4 v[160:163], v1, s[54:55]
	global_load_dwordx4 v[164:167], v1, s[54:55] offset:256
	s_add_u32 s54, s54, 0x6000
	s_addc_u32 s55, s55, 0
	global_load_dwordx4 v[168:171], v1, s[54:55]
	global_load_dwordx4 v[172:175], v1, s[54:55] offset:256
	s_add_u32 s54, s54, 0x6000
	s_addc_u32 s55, s55, 0
	global_load_dwordx4 v[176:179], v1, s[54:55]
	global_load_dwordx4 v[180:183], v1, s[54:55] offset:256
	s_add_u32 s54, s54, 0x6000
	s_addc_u32 s55, s55, 0
	global_load_dwordx4 v[184:187], v1, s[54:55]
	global_load_dwordx4 v[188:191], v1, s[54:55] offset:256
	s_add_u32 s54, s54, 0x6000
	s_addc_u32 s55, s55, 0
	global_load_dwordx4 v[192:195], v1, s[54:55]
	global_load_dwordx4 v[196:199], v1, s[54:55] offset:256
	s_lshl_b32 s53, s5, 3
	s_add_i32 s53, s53, 0x2000
	s_mul_i32 s53, s53, 0x3000
	s_lshl_b32 s52, s6, 4
	s_add_u32 s53, s53, s52
	s_add_u32 s30, s22, s53
	s_addc_u32 s31, s23, 0
	s_waitcnt vmcnt(14)
	v_lshlrev_b32_e32 v120, 16, v136
	v_and_b32_e32 v121, 0xffff0000, v136
	v_lshlrev_b32_e32 v122, 16, v137
	v_and_b32_e32 v123, 0xffff0000, v137
	v_lshlrev_b32_e32 v124, 16, v138
	v_and_b32_e32 v125, 0xffff0000, v138
	v_lshlrev_b32_e32 v126, 16, v139
	v_and_b32_e32 v127, 0xffff0000, v139
	v_lshlrev_b32_e32 v128, 16, v140
	v_and_b32_e32 v129, 0xffff0000, v140
	v_lshlrev_b32_e32 v130, 16, v141
	v_and_b32_e32 v131, 0xffff0000, v141
	v_lshlrev_b32_e32 v132, 16, v142
	v_and_b32_e32 v133, 0xffff0000, v142
	v_lshlrev_b32_e32 v134, 16, v143
	v_and_b32_e32 v135, 0xffff0000, v143
	v_pk_fma_f32 v[242:243], v[88:89], v[24:25], v[72:73]
	v_pk_fma_f32 v[224:225], v[96:97], v[32:33], v[80:81]
	v_pk_fma_f32 v[244:245], v[90:91], v[26:27], v[74:75]
	v_pk_fma_f32 v[226:227], v[98:99], v[34:35], v[82:83]
	v_pk_fma_f32 v[246:247], v[92:93], v[28:29], v[76:77]
	v_pk_fma_f32 v[228:229], v[100:101], v[36:37], v[84:85]
	v_pk_fma_f32 v[248:249], v[94:95], v[30:31], v[78:79]
	v_pk_fma_f32 v[230:231], v[102:103], v[38:39], v[86:87]
	v_pk_fma_f32 v[242:243], v[104:105], v[40:41], v[242:243]
	v_pk_fma_f32 v[224:225], v[112:113], v[48:49], v[224:225]
	v_pk_fma_f32 v[244:245], v[106:107], v[42:43], v[244:245]
	v_pk_fma_f32 v[226:227], v[114:115], v[50:51], v[226:227]
	v_pk_fma_f32 v[246:247], v[108:109], v[44:45], v[246:247]
	v_pk_fma_f32 v[228:229], v[116:117], v[52:53], v[228:229]
	v_pk_fma_f32 v[248:249], v[110:111], v[46:47], v[248:249]
	v_pk_fma_f32 v[230:231], v[118:119], v[54:55], v[230:231]
	v_pk_fma_f32 v[242:243], v[120:121], v[56:57], v[242:243]
	v_pk_fma_f32 v[224:225], v[128:129], v[64:65], v[224:225]
	v_pk_fma_f32 v[244:245], v[122:123], v[58:59], v[244:245]
	v_pk_fma_f32 v[226:227], v[130:131], v[66:67], v[226:227]
	v_pk_fma_f32 v[246:247], v[124:125], v[60:61], v[246:247]
	v_pk_fma_f32 v[228:229], v[132:133], v[68:69], v[228:229]
	v_pk_fma_f32 v[248:249], v[126:127], v[62:63], v[248:249]
	v_pk_fma_f32 v[230:231], v[134:135], v[70:71], v[230:231]
	v_pk_mul_f32 v[200:201], v[242:243], v[242:243]
; __device__ __forceinline__ u32x4 pack8(const float (&f)[8]) { u32x4 w; w.x = pk2(f[0], f[1]); w.y = pk2(f[2], f[3]); w.z = pk2(f[4], f[5]); w.w = pk2(f[6], f[7]); return w; }
; __device__ __forceinline__ float gelu_tanh(float x) { const float y = 1.5957691216f * (x + 0.044715f * x * x * x); return x * __builtin_amdgcn_rcpf(1.0f + __expf(-y)); }
; __device__ __forceinline__ void phase_ffnconv(const Params& p) {
;     ...
;         for (int rs = slot; rs < 1024; rs += 170) {
;             const int row = MPROMPT + rs, t = rs & 7, b = rs >> 3;
;             float xg[3][8], xv[3][8];
; #pragma unroll
;             for (int k = 0; k < 3; ++k) { const int tt = t - 2 + k;
;                 if (tt >= 0) { unpack8(*(const u32x4*)(UP + (size_t)(row - 2 + k) * 2 * DFF + colg), xg[k]); unpack8(*(const u32x4*)(UP + (size_t)(row - 2 + k) * 2 * DFF + colg + 128), xv[k]); }
;                 else { const float* sp = p.in[I_SFCONV] + ((size_t)b * 2 + (2 + tt)) * 2 * DFF; ld8f(sp + j0, xg[k]); ld8f(sp + DFF + j0, xv[k]); } }
;             float f[8];
; #pragma unroll
;             for (int e = 0; e < 8; ++e) { const float cg_ = bg[e] + xg[0][e] * wg[0][e] + xg[1][e] * wg[1][e] + xg[2][e] * wg[2][e];
;                 const float cv_ = bv[e] + xv[0][e] * wv[0][e] + xv[1][e] * wv[1][e] + xv[2][e] * wv[2][e]; f[e] = gelu_tanh(cg_) * cv_; }
;             *(u32x4*)(F + (size_t)row * DFF + j0) = pack8(f);
	v_pk_mul_f32 v[202:203], v[244:245], v[244:245]
	v_pk_mul_f32 v[204:205], v[246:247], v[246:247]
	v_pk_mul_f32 v[206:207], v[248:249], v[248:249]
	v_pk_fma_f32 v[200:201], v[200:201], s[26:27], v[4:5]
	v_pk_fma_f32 v[202:203], v[202:203], s[26:27], v[4:5]
	v_pk_fma_f32 v[204:205], v[204:205], s[26:27], v[4:5]
	v_pk_fma_f32 v[206:207], v[206:207], s[26:27], v[4:5]
	v_pk_mul_f32 v[200:201], v[242:243], v[200:201]
	v_pk_mul_f32 v[202:203], v[244:245], v[202:203]
	v_pk_mul_f32 v[204:205], v[246:247], v[204:205]
	v_pk_mul_f32 v[206:207], v[248:249], v[206:207]
	v_exp_f32_e32 v200, v200
	v_exp_f32_e32 v201, v201
	v_exp_f32_e32 v202, v202
	v_exp_f32_e32 v203, v203
	v_exp_f32_e32 v204, v204
	v_exp_f32_e32 v205, v205
	v_exp_f32_e32 v206, v206
	v_exp_f32_e32 v207, v207
	v_pk_add_f32 v[200:201], v[200:201], s[28:29]
	v_pk_add_f32 v[202:203], v[202:203], s[28:29]
	v_pk_add_f32 v[204:205], v[204:205], s[28:29]
	v_pk_add_f32 v[206:207], v[206:207], s[28:29]
	v_rcp_f32_e32 v200, v200
	v_rcp_f32_e32 v201, v201
	v_rcp_f32_e32 v202, v202
	v_rcp_f32_e32 v203, v203
	v_rcp_f32_e32 v204, v204
	v_rcp_f32_e32 v205, v205
	v_rcp_f32_e32 v206, v206
	v_rcp_f32_e32 v207, v207
	v_pk_mul_f32 v[200:201], v[242:243], v[200:201]
	v_pk_mul_f32 v[202:203], v[244:245], v[202:203]
	v_pk_mul_f32 v[204:205], v[246:247], v[204:205]
	v_pk_mul_f32 v[206:207], v[248:249], v[206:207]
	v_pk_mul_f32 v[200:201], v[200:201], v[224:225]
	v_pk_mul_f32 v[202:203], v[202:203], v[226:227]
	v_pk_mul_f32 v[204:205], v[204:205], v[228:229]
	v_pk_mul_f32 v[206:207], v[206:207], v[230:231]
	v_cvt_pk_bf16_f32 v250, v200, v201
	v_cvt_pk_bf16_f32 v251, v202, v203
	v_cvt_pk_bf16_f32 v252, v204, v205
	v_cvt_pk_bf16_f32 v253, v206, v207
	global_store_dwordx4 v3, v[250:253], s[30:31]
	s_add_u32 s30, s30, 0x3000
	s_addc_u32 s31, s31, 0
	s_waitcnt vmcnt(12)
	v_lshlrev_b32_e32 v88, 16, v144
	v_and_b32_e32 v89, 0xffff0000, v144
	v_lshlrev_b32_e32 v90, 16, v145
	v_and_b32_e32 v91, 0xffff0000, v145
	v_lshlrev_b32_e32 v92, 16, v146
	v_and_b32_e32 v93, 0xffff0000, v146
	v_lshlrev_b32_e32 v94, 16, v147
	v_and_b32_e32 v95, 0xffff0000, v147
	v_lshlrev_b32_e32 v96, 16, v148
	v_and_b32_e32 v97, 0xffff0000, v148
	v_lshlrev_b32_e32 v98, 16, v149
	v_and_b32_e32 v99, 0xffff0000, v149
	v_lshlrev_b32_e32 v100, 16, v150
	v_and_b32_e32 v101, 0xffff0000, v150
	v_lshlrev_b32_e32 v102, 16, v151
	v_and_b32_e32 v103, 0xffff0000, v151
	v_pk_fma_f32 v[242:243], v[104:105], v[24:25], v[72:73]
	v_pk_fma_f32 v[224:225], v[112:113], v[32:33], v[80:81]
	v_pk_fma_f32 v[244:245], v[106:107], v[26:27], v[74:75]
	v_pk_fma_f32 v[226:227], v[114:115], v[34:35], v[82:83]
	v_pk_fma_f32 v[246:247], v[108:109], v[28:29], v[76:77]
	v_pk_fma_f32 v[228:229], v[116:117], v[36:37], v[84:85]
	v_pk_fma_f32 v[248:249], v[110:111], v[30:31], v[78:79]
	v_pk_fma_f32 v[230:231], v[118:119], v[38:39], v[86:87]
	v_pk_fma_f32 v[242:243], v[120:121], v[40:41], v[242:243]
	v_pk_fma_f32 v[224:225], v[128:129], v[48:49], v[224:225]
	v_pk_fma_f32 v[244:245], v[122:123], v[42:43], v[244:245]
	v_pk_fma_f32 v[226:227], v[130:131], v[50:51], v[226:227]
	v_pk_fma_f32 v[246:247], v[124:125], v[44:45], v[246:247]
	v_pk_fma_f32 v[228:229], v[132:133], v[52:53], v[228:229]
	v_pk_fma_f32 v[248:249], v[126:127], v[46:47], v[248:249]
	v_pk_fma_f32 v[230:231], v[134:135], v[54:55], v[230:231]
	v_pk_fma_f32 v[242:243], v[88:89], v[56:57], v[242:243]
	v_pk_fma_f32 v[224:225], v[96:97], v[64:65], v[224:225]
	v_pk_fma_f32 v[244:245], v[90:91], v[58:59], v[244:245]
	v_pk_fma_f32 v[226:227], v[98:99], v[66:67], v[226:227]
	v_pk_fma_f32 v[246:247], v[92:93], v[60:61], v[246:247]
	v_pk_fma_f32 v[228:229], v[100:101], v[68:69], v[228:229]
	v_pk_fma_f32 v[248:249], v[94:95], v[62:63], v[248:249]
	v_pk_fma_f32 v[230:231], v[102:103], v[70:71], v[230:231]
	v_pk_mul_f32 v[200:201], v[242:243], v[242:243]
	v_pk_mul_f32 v[202:203], v[244:245], v[244:245]
	v_pk_mul_f32 v[204:205], v[246:247], v[246:247]
	v_pk_mul_f32 v[206:207], v[248:249], v[248:249]
	v_pk_fma_f32 v[200:201], v[200:201], s[26:27], v[4:5]
	v_pk_fma_f32 v[202:203], v[202:203], s[26:27], v[4:5]
	v_pk_fma_f32 v[204:205], v[204:205], s[26:27], v[4:5]
	v_pk_fma_f32 v[206:207], v[206:207], s[26:27], v[4:5]
	v_pk_mul_f32 v[200:201], v[242:243], v[200:201]
	v_pk_mul_f32 v[202:203], v[244:245], v[202:203]
	v_pk_mul_f32 v[204:205], v[246:247], v[204:205]
	v_pk_mul_f32 v[206:207], v[248:249], v[206:207]
	v_exp_f32_e32 v200, v200
	v_exp_f32_e32 v201, v201
	v_exp_f32_e32 v202, v202
	v_exp_f32_e32 v203, v203
	v_exp_f32_e32 v204, v204
	v_exp_f32_e32 v205, v205
	v_exp_f32_e32 v206, v206
	v_exp_f32_e32 v207, v207
	v_pk_add_f32 v[200:201], v[200:201], s[28:29]
	v_pk_add_f32 v[202:203], v[202:203], s[28:29]
	v_pk_add_f32 v[204:205], v[204:205], s[28:29]
	v_pk_add_f32 v[206:207], v[206:207], s[28:29]
	v_rcp_f32_e32 v200, v200
	v_rcp_f32_e32 v201, v201
	v_rcp_f32_e32 v202, v202
	v_rcp_f32_e32 v203, v203
	v_rcp_f32_e32 v204, v204
	v_rcp_f32_e32 v205, v205
	v_rcp_f32_e32 v206, v206
	v_rcp_f32_e32 v207, v207
	v_pk_mul_f32 v[200:201], v[242:243], v[200:201]
	v_pk_mul_f32 v[202:203], v[244:245], v[202:203]
	v_pk_mul_f32 v[204:205], v[246:247], v[204:205]
	v_pk_mul_f32 v[206:207], v[248:249], v[206:207]
	v_pk_mul_f32 v[200:201], v[200:201], v[224:225]
	v_pk_mul_f32 v[202:203], v[202:203], v[226:227]
	v_pk_mul_f32 v[204:205], v[204:205], v[228:229]
	v_pk_mul_f32 v[206:207], v[206:207], v[230:231]
	v_cvt_pk_bf16_f32 v250, v200, v201
	v_cvt_pk_bf16_f32 v251, v202, v203
	v_cvt_pk_bf16_f32 v252, v204, v205
	v_cvt_pk_bf16_f32 v253, v206, v207
	global_store_dwordx4 v3, v[250:253], s[30:31]
	s_add_u32 s30, s30, 0x3000
	s_addc_u32 s31, s31, 0
	s_waitcnt vmcnt(10)
; __device__ __forceinline__ u32x4 pack8(const float (&f)[8]) { u32x4 w; w.x = pk2(f[0], f[1]); w.y = pk2(f[2], f[3]); w.z = pk2(f[4], f[5]); w.w = pk2(f[6], f[7]); return w; }
; __device__ __forceinline__ float gelu_tanh(float x) { const float y = 1.5957691216f * (x + 0.044715f * x * x * x); return x * __builtin_amdgcn_rcpf(1.0f + __expf(-y)); }
; __device__ __forceinline__ void phase_ffnconv(const Params& p) {
;     ...
;         for (int rs = slot; rs < 1024; rs += 170) {
;             const int row = MPROMPT + rs, t = rs & 7, b = rs >> 3;
;             float xg[3][8], xv[3][8];
; #pragma unroll
;             for (int k = 0; k < 3; ++k) { const int tt = t - 2 + k;
;                 if (tt >= 0) { unpack8(*(const u32x4*)(UP + (size_t)(row - 2 + k) * 2 * DFF + colg), xg[k]); unpack8(*(const u32x4*)(UP + (size_t)(row - 2 + k) * 2 * DFF + colg + 128), xv[k]); }
;                 else { const float* sp = p.in[I_SFCONV] + ((size_t)b * 2 + (2 + tt)) * 2 * DFF; ld8f(sp + j0, xg[k]); ld8f(sp + DFF + j0, xv[k]); } }
;             float f[8];
; #pragma unroll
;             for (int e = 0; e < 8; ++e) { const float cg_ = bg[e] + xg[0][e] * wg[0][e] + xg[1][e] * wg[1][e] + xg[2][e] * wg[2][e];
;                 const float cv_ = bv[e] + xv[0][e] * wv[0][e] + xv[1][e] * wv[1][e] + xv[2][e] * wv[2][e]; f[e] = gelu_tanh(cg_) * cv_; }
;             *(u32x4*)(F + (size_t)row * DFF + j0) = pack8(f);
	v_lshlrev_b32_e32 v104, 16, v152
	v_and_b32_e32 v105, 0xffff0000, v152
	v_lshlrev_b32_e32 v106, 16, v153
	v_and_b32_e32 v107, 0xffff0000, v153
	v_lshlrev_b32_e32 v108, 16, v154
	v_and_b32_e32 v109, 0xffff0000, v154
	v_lshlrev_b32_e32 v110, 16, v155
	v_and_b32_e32 v111, 0xffff0000, v155
	v_lshlrev_b32_e32 v112, 16, v156
	v_and_b32_e32 v113, 0xffff0000, v156
	v_lshlrev_b32_e32 v114, 16, v157
	v_and_b32_e32 v115, 0xffff0000, v157
	v_lshlrev_b32_e32 v116, 16, v158
	v_and_b32_e32 v117, 0xffff0000, v158
	v_lshlrev_b32_e32 v118, 16, v159
	v_and_b32_e32 v119, 0xffff0000, v159
	v_pk_fma_f32 v[242:243], v[120:121], v[24:25], v[72:73]
	v_pk_fma_f32 v[224:225], v[128:129], v[32:33], v[80:81]
	v_pk_fma_f32 v[244:245], v[122:123], v[26:27], v[74:75]
	v_pk_fma_f32 v[226:227], v[130:131], v[34:35], v[82:83]
	v_pk_fma_f32 v[246:247], v[124:125], v[28:29], v[76:77]
	v_pk_fma_f32 v[228:229], v[132:133], v[36:37], v[84:85]
	v_pk_fma_f32 v[248:249], v[126:127], v[30:31], v[78:79]
	v_pk_fma_f32 v[230:231], v[134:135], v[38:39], v[86:87]
	v_pk_fma_f32 v[242:243], v[88:89], v[40:41], v[242:243]
	v_pk_fma_f32 v[224:225], v[96:97], v[48:49], v[224:225]
	v_pk_fma_f32 v[244:245], v[90:91], v[42:43], v[244:245]
	v_pk_fma_f32 v[226:227], v[98:99], v[50:51], v[226:227]
	v_pk_fma_f32 v[246:247], v[92:93], v[44:45], v[246:247]
	v_pk_fma_f32 v[228:229], v[100:101], v[52:53], v[228:229]
	v_pk_fma_f32 v[248:249], v[94:95], v[46:47], v[248:249]
	v_pk_fma_f32 v[230:231], v[102:103], v[54:55], v[230:231]
	v_pk_fma_f32 v[242:243], v[104:105], v[56:57], v[242:243]
	v_pk_fma_f32 v[224:225], v[112:113], v[64:65], v[224:225]
	v_pk_fma_f32 v[244:245], v[106:107], v[58:59], v[244:245]
	v_pk_fma_f32 v[226:227], v[114:115], v[66:67], v[226:227]
	v_pk_fma_f32 v[246:247], v[108:109], v[60:61], v[246:247]
	v_pk_fma_f32 v[228:229], v[116:117], v[68:69], v[228:229]
	v_pk_fma_f32 v[248:249], v[110:111], v[62:63], v[248:249]
	v_pk_fma_f32 v[230:231], v[118:119], v[70:71], v[230:231]
	v_pk_mul_f32 v[200:201], v[242:243], v[242:243]
	v_pk_mul_f32 v[202:203], v[244:245], v[244:245]
	v_pk_mul_f32 v[204:205], v[246:247], v[246:247]
	v_pk_mul_f32 v[206:207], v[248:249], v[248:249]
	v_pk_fma_f32 v[200:201], v[200:201], s[26:27], v[4:5]
	v_pk_fma_f32 v[202:203], v[202:203], s[26:27], v[4:5]
	v_pk_fma_f32 v[204:205], v[204:205], s[26:27], v[4:5]
	v_pk_fma_f32 v[206:207], v[206:207], s[26:27], v[4:5]
	v_pk_mul_f32 v[200:201], v[242:243], v[200:201]
	v_pk_mul_f32 v[202:203], v[244:245], v[202:203]
	v_pk_mul_f32 v[204:205], v[246:247], v[204:205]
	v_pk_mul_f32 v[206:207], v[248:249], v[206:207]
	v_exp_f32_e32 v200, v200
	v_exp_f32_e32 v201, v201
	v_exp_f32_e32 v202, v202
	v_exp_f32_e32 v203, v203
	v_exp_f32_e32 v204, v204
	v_exp_f32_e32 v205, v205
	v_exp_f32_e32 v206, v206
	v_exp_f32_e32 v207, v207
	v_pk_add_f32 v[200:201], v[200:201], s[28:29]
	v_pk_add_f32 v[202:203], v[202:203], s[28:29]
	v_pk_add_f32 v[204:205], v[204:205], s[28:29]
	v_pk_add_f32 v[206:207], v[206:207], s[28:29]
	v_rcp_f32_e32 v200, v200
	v_rcp_f32_e32 v201, v201
	v_rcp_f32_e32 v202, v202
	v_rcp_f32_e32 v203, v203
	v_rcp_f32_e32 v204, v204
	v_rcp_f32_e32 v205, v205
	v_rcp_f32_e32 v206, v206
	v_rcp_f32_e32 v207, v207
	v_pk_mul_f32 v[200:201], v[242:243], v[200:201]
	v_pk_mul_f32 v[202:203], v[244:245], v[202:203]
	v_pk_mul_f32 v[204:205], v[246:247], v[204:205]
	v_pk_mul_f32 v[206:207], v[248:249], v[206:207]
	v_pk_mul_f32 v[200:201], v[200:201], v[224:225]
	v_pk_mul_f32 v[202:203], v[202:203], v[226:227]
	v_pk_mul_f32 v[204:205], v[204:205], v[228:229]
	v_pk_mul_f32 v[206:207], v[206:207], v[230:231]
	v_cvt_pk_bf16_f32 v250, v200, v201
	v_cvt_pk_bf16_f32 v251, v202, v203
	v_cvt_pk_bf16_f32 v252, v204, v205
	v_cvt_pk_bf16_f32 v253, v206, v207
	global_store_dwordx4 v3, v[250:253], s[30:31]
	s_add_u32 s30, s30, 0x3000
	s_addc_u32 s31, s31, 0
	s_waitcnt vmcnt(8)
	v_lshlrev_b32_e32 v120, 16, v160
	v_and_b32_e32 v121, 0xffff0000, v160
	v_lshlrev_b32_e32 v122, 16, v161
	v_and_b32_e32 v123, 0xffff0000, v161
	v_lshlrev_b32_e32 v124, 16, v162
	v_and_b32_e32 v125, 0xffff0000, v162
	v_lshlrev_b32_e32 v126, 16, v163
	v_and_b32_e32 v127, 0xffff0000, v163
	v_lshlrev_b32_e32 v128, 16, v164
	v_and_b32_e32 v129, 0xffff0000, v164
	v_lshlrev_b32_e32 v130, 16, v165
	v_and_b32_e32 v131, 0xffff0000, v165
	v_lshlrev_b32_e32 v132, 16, v166
	v_and_b32_e32 v133, 0xffff0000, v166
	v_lshlrev_b32_e32 v134, 16, v167
	v_and_b32_e32 v135, 0xffff0000, v167
	v_pk_fma_f32 v[242:243], v[88:89], v[24:25], v[72:73]
	v_pk_fma_f32 v[224:225], v[96:97], v[32:33], v[80:81]
	v_pk_fma_f32 v[244:245], v[90:91], v[26:27], v[74:75]
	v_pk_fma_f32 v[226:227], v[98:99], v[34:35], v[82:83]
	v_pk_fma_f32 v[246:247], v[92:93], v[28:29], v[76:77]
	v_pk_fma_f32 v[228:229], v[100:101], v[36:37], v[84:85]
	v_pk_fma_f32 v[248:249], v[94:95], v[30:31], v[78:79]
	v_pk_fma_f32 v[230:231], v[102:103], v[38:39], v[86:87]
	v_pk_fma_f32 v[242:243], v[104:105], v[40:41], v[242:243]
	v_pk_fma_f32 v[224:225], v[112:113], v[48:49], v[224:225]
	v_pk_fma_f32 v[244:245], v[106:107], v[42:43], v[244:245]
	v_pk_fma_f32 v[226:227], v[114:115], v[50:51], v[226:227]
	v_pk_fma_f32 v[246:247], v[108:109], v[44:45], v[246:247]
	v_pk_fma_f32 v[228:229], v[116:117], v[52:53], v[228:229]
	v_pk_fma_f32 v[248:249], v[110:111], v[46:47], v[248:249]
	v_pk_fma_f32 v[230:231], v[118:119], v[54:55], v[230:231]
	v_pk_fma_f32 v[242:243], v[120:121], v[56:57], v[242:243]
	v_pk_fma_f32 v[224:225], v[128:129], v[64:65], v[224:225]
	v_pk_fma_f32 v[244:245], v[122:123], v[58:59], v[244:245]
	v_pk_fma_f32 v[226:227], v[130:131], v[66:67], v[226:227]
	v_pk_fma_f32 v[246:247], v[124:125], v[60:61], v[246:247]
; __device__ __forceinline__ u32x4 pack8(const float (&f)[8]) { u32x4 w; w.x = pk2(f[0], f[1]); w.y = pk2(f[2], f[3]); w.z = pk2(f[4], f[5]); w.w = pk2(f[6], f[7]); return w; }
; __device__ __forceinline__ float gelu_tanh(float x) { const float y = 1.5957691216f * (x + 0.044715f * x * x * x); return x * __builtin_amdgcn_rcpf(1.0f + __expf(-y)); }
; __device__ __forceinline__ void phase_ffnconv(const Params& p) {
;     ...
;         for (int rs = slot; rs < 1024; rs += 170) {
;             const int row = MPROMPT + rs, t = rs & 7, b = rs >> 3;
;             float xg[3][8], xv[3][8];
; #pragma unroll
;             for (int k = 0; k < 3; ++k) { const int tt = t - 2 + k;
;                 if (tt >= 0) { unpack8(*(const u32x4*)(UP + (size_t)(row - 2 + k) * 2 * DFF + colg), xg[k]); unpack8(*(const u32x4*)(UP + (size_t)(row - 2 + k) * 2 * DFF + colg + 128), xv[k]); }
;                 else { const float* sp = p.in[I_SFCONV] + ((size_t)b * 2 + (2 + tt)) * 2 * DFF; ld8f(sp + j0, xg[k]); ld8f(sp + DFF + j0, xv[k]); } }
;             float f[8];
; #pragma unroll
;             for (int e = 0; e < 8; ++e) { const float cg_ = bg[e] + xg[0][e] * wg[0][e] + xg[1][e] * wg[1][e] + xg[2][e] * wg[2][e];
;                 const float cv_ = bv[e] + xv[0][e] * wv[0][e] + xv[1][e] * wv[1][e] + xv[2][e] * wv[2][e]; f[e] = gelu_tanh(cg_) * cv_; }
;             *(u32x4*)(F + (size_t)row * DFF + j0) = pack8(f);
	v_pk_fma_f32 v[228:229], v[132:133], v[68:69], v[228:229]
	v_pk_fma_f32 v[248:249], v[126:127], v[62:63], v[248:249]
	v_pk_fma_f32 v[230:231], v[134:135], v[70:71], v[230:231]
	v_pk_mul_f32 v[200:201], v[242:243], v[242:243]
	v_pk_mul_f32 v[202:203], v[244:245], v[244:245]
	v_pk_mul_f32 v[204:205], v[246:247], v[246:247]
	v_pk_mul_f32 v[206:207], v[248:249], v[248:249]
	v_pk_fma_f32 v[200:201], v[200:201], s[26:27], v[4:5]
	v_pk_fma_f32 v[202:203], v[202:203], s[26:27], v[4:5]
	v_pk_fma_f32 v[204:205], v[204:205], s[26:27], v[4:5]
	v_pk_fma_f32 v[206:207], v[206:207], s[26:27], v[4:5]
	v_pk_mul_f32 v[200:201], v[242:243], v[200:201]
	v_pk_mul_f32 v[202:203], v[244:245], v[202:203]
	v_pk_mul_f32 v[204:205], v[246:247], v[204:205]
	v_pk_mul_f32 v[206:207], v[248:249], v[206:207]
	v_exp_f32_e32 v200, v200
	v_exp_f32_e32 v201, v201
	v_exp_f32_e32 v202, v202
	v_exp_f32_e32 v203, v203
	v_exp_f32_e32 v204, v204
	v_exp_f32_e32 v205, v205
	v_exp_f32_e32 v206, v206
	v_exp_f32_e32 v207, v207
	v_pk_add_f32 v[200:201], v[200:201], s[28:29]
	v_pk_add_f32 v[202:203], v[202:203], s[28:29]
	v_pk_add_f32 v[204:205], v[204:205], s[28:29]
	v_pk_add_f32 v[206:207], v[206:207], s[28:29]
	v_rcp_f32_e32 v200, v200
	v_rcp_f32_e32 v201, v201
	v_rcp_f32_e32 v202, v202
	v_rcp_f32_e32 v203, v203
	v_rcp_f32_e32 v204, v204
	v_rcp_f32_e32 v205, v205
	v_rcp_f32_e32 v206, v206
	v_rcp_f32_e32 v207, v207
	v_pk_mul_f32 v[200:201], v[242:243], v[200:201]
	v_pk_mul_f32 v[202:203], v[244:245], v[202:203]
	v_pk_mul_f32 v[204:205], v[246:247], v[204:205]
	v_pk_mul_f32 v[206:207], v[248:249], v[206:207]
	v_pk_mul_f32 v[200:201], v[200:201], v[224:225]
	v_pk_mul_f32 v[202:203], v[202:203], v[226:227]
	v_pk_mul_f32 v[204:205], v[204:205], v[228:229]
	v_pk_mul_f32 v[206:207], v[206:207], v[230:231]
	v_cvt_pk_bf16_f32 v250, v200, v201
	v_cvt_pk_bf16_f32 v251, v202, v203
	v_cvt_pk_bf16_f32 v252, v204, v205
	v_cvt_pk_bf16_f32 v253, v206, v207
	global_store_dwordx4 v3, v[250:253], s[30:31]
	s_add_u32 s30, s30, 0x3000
	s_addc_u32 s31, s31, 0
	s_waitcnt vmcnt(6)
	v_lshlrev_b32_e32 v88, 16, v168
	v_and_b32_e32 v89, 0xffff0000, v168
	v_lshlrev_b32_e32 v90, 16, v169
	v_and_b32_e32 v91, 0xffff0000, v169
	v_lshlrev_b32_e32 v92, 16, v170
	v_and_b32_e32 v93, 0xffff0000, v170
	v_lshlrev_b32_e32 v94, 16, v171
	v_and_b32_e32 v95, 0xffff0000, v171
	v_lshlrev_b32_e32 v96, 16, v172
	v_and_b32_e32 v97, 0xffff0000, v172
	v_lshlrev_b32_e32 v98, 16, v173
	v_and_b32_e32 v99, 0xffff0000, v173
	v_lshlrev_b32_e32 v100, 16, v174
	v_and_b32_e32 v101, 0xffff0000, v174
	v_lshlrev_b32_e32 v102, 16, v175
	v_and_b32_e32 v103, 0xffff0000, v175
	v_pk_fma_f32 v[242:243], v[104:105], v[24:25], v[72:73]
	v_pk_fma_f32 v[224:225], v[112:113], v[32:33], v[80:81]
	v_pk_fma_f32 v[244:245], v[106:107], v[26:27], v[74:75]
	v_pk_fma_f32 v[226:227], v[114:115], v[34:35], v[82:83]
	v_pk_fma_f32 v[246:247], v[108:109], v[28:29], v[76:77]
	v_pk_fma_f32 v[228:229], v[116:117], v[36:37], v[84:85]
	v_pk_fma_f32 v[248:249], v[110:111], v[30:31], v[78:79]
	v_pk_fma_f32 v[230:231], v[118:119], v[38:39], v[86:87]
	v_pk_fma_f32 v[242:243], v[120:121], v[40:41], v[242:243]
	v_pk_fma_f32 v[224:225], v[128:129], v[48:49], v[224:225]
	v_pk_fma_f32 v[244:245], v[122:123], v[42:43], v[244:245]
	v_pk_fma_f32 v[226:227], v[130:131], v[50:51], v[226:227]
	v_pk_fma_f32 v[246:247], v[124:125], v[44:45], v[246:247]
	v_pk_fma_f32 v[228:229], v[132:133], v[52:53], v[228:229]
	v_pk_fma_f32 v[248:249], v[126:127], v[46:47], v[248:249]
	v_pk_fma_f32 v[230:231], v[134:135], v[54:55], v[230:231]
	v_pk_fma_f32 v[242:243], v[88:89], v[56:57], v[242:243]
	v_pk_fma_f32 v[224:225], v[96:97], v[64:65], v[224:225]
	v_pk_fma_f32 v[244:245], v[90:91], v[58:59], v[244:245]
	v_pk_fma_f32 v[226:227], v[98:99], v[66:67], v[226:227]
	v_pk_fma_f32 v[246:247], v[92:93], v[60:61], v[246:247]
	v_pk_fma_f32 v[228:229], v[100:101], v[68:69], v[228:229]
	v_pk_fma_f32 v[248:249], v[94:95], v[62:63], v[248:249]
	v_pk_fma_f32 v[230:231], v[102:103], v[70:71], v[230:231]
	v_pk_mul_f32 v[200:201], v[242:243], v[242:243]
	v_pk_mul_f32 v[202:203], v[244:245], v[244:245]
	v_pk_mul_f32 v[204:205], v[246:247], v[246:247]
	v_pk_mul_f32 v[206:207], v[248:249], v[248:249]
	v_pk_fma_f32 v[200:201], v[200:201], s[26:27], v[4:5]
	v_pk_fma_f32 v[202:203], v[202:203], s[26:27], v[4:5]
	v_pk_fma_f32 v[204:205], v[204:205], s[26:27], v[4:5]
	v_pk_fma_f32 v[206:207], v[206:207], s[26:27], v[4:5]
	v_pk_mul_f32 v[200:201], v[242:243], v[200:201]
	v_pk_mul_f32 v[202:203], v[244:245], v[202:203]
	v_pk_mul_f32 v[204:205], v[246:247], v[204:205]
	v_pk_mul_f32 v[206:207], v[248:249], v[206:207]
	v_exp_f32_e32 v200, v200
	v_exp_f32_e32 v201, v201
	v_exp_f32_e32 v202, v202
	v_exp_f32_e32 v203, v203
	v_exp_f32_e32 v204, v204
	v_exp_f32_e32 v205, v205
	v_exp_f32_e32 v206, v206
	v_exp_f32_e32 v207, v207
	v_pk_add_f32 v[200:201], v[200:201], s[28:29]
	v_pk_add_f32 v[202:203], v[202:203], s[28:29]
	v_pk_add_f32 v[204:205], v[204:205], s[28:29]
	v_pk_add_f32 v[206:207], v[206:207], s[28:29]
	v_rcp_f32_e32 v200, v200
	v_rcp_f32_e32 v201, v201
	v_rcp_f32_e32 v202, v202
	v_rcp_f32_e32 v203, v203
	v_rcp_f32_e32 v204, v204
	v_rcp_f32_e32 v205, v205
	v_rcp_f32_e32 v206, v206
	v_rcp_f32_e32 v207, v207
	v_pk_mul_f32 v[200:201], v[242:243], v[200:201]
	v_pk_mul_f32 v[202:203], v[244:245], v[202:203]
	v_pk_mul_f32 v[204:205], v[246:247], v[204:205]
	v_pk_mul_f32 v[206:207], v[248:249], v[206:207]
	v_pk_mul_f32 v[200:201], v[200:201], v[224:225]
	v_pk_mul_f32 v[202:203], v[202:203], v[226:227]
	v_pk_mul_f32 v[204:205], v[204:205], v[228:229]
	v_pk_mul_f32 v[206:207], v[206:207], v[230:231]
	v_cvt_pk_bf16_f32 v250, v200, v201
	v_cvt_pk_bf16_f32 v251, v202, v203
	v_cvt_pk_bf16_f32 v252, v204, v205
	v_cvt_pk_bf16_f32 v253, v206, v207
	global_store_dwordx4 v3, v[250:253], s[30:31]
	s_add_u32 s30, s30, 0x3000
	s_addc_u32 s31, s31, 0
	s_waitcnt vmcnt(4)
; __device__ __forceinline__ u32x4 pack8(const float (&f)[8]) { u32x4 w; w.x = pk2(f[0], f[1]); w.y = pk2(f[2], f[3]); w.z = pk2(f[4], f[5]); w.w = pk2(f[6], f[7]); return w; }
; __device__ __forceinline__ float gelu_tanh(float x) { const float y = 1.5957691216f * (x + 0.044715f * x * x * x); return x * __builtin_amdgcn_rcpf(1.0f + __expf(-y)); }
; __device__ __forceinline__ void phase_ffnconv(const Params& p) {
;     ...
;         for (int rs = slot; rs < 1024; rs += 170) {
;             const int row = MPROMPT + rs, t = rs & 7, b = rs >> 3;
;             float xg[3][8], xv[3][8];
; #pragma unroll
;             for (int k = 0; k < 3; ++k) { const int tt = t - 2 + k;
;                 if (tt >= 0) { unpack8(*(const u32x4*)(UP + (size_t)(row - 2 + k) * 2 * DFF + colg), xg[k]); unpack8(*(const u32x4*)(UP + (size_t)(row - 2 + k) * 2 * DFF + colg + 128), xv[k]); }
;                 else { const float* sp = p.in[I_SFCONV] + ((size_t)b * 2 + (2 + tt)) * 2 * DFF; ld8f(sp + j0, xg[k]); ld8f(sp + DFF + j0, xv[k]); } }
;             float f[8];
; #pragma unroll
;             for (int e = 0; e < 8; ++e) { const float cg_ = bg[e] + xg[0][e] * wg[0][e] + xg[1][e] * wg[1][e] + xg[2][e] * wg[2][e];
;                 const float cv_ = bv[e] + xv[0][e] * wv[0][e] + xv[1][e] * wv[1][e] + xv[2][e] * wv[2][e]; f[e] = gelu_tanh(cg_) * cv_; }
;             *(u32x4*)(F + (size_t)row * DFF + j0) = pack8(f);
	v_lshlrev_b32_e32 v104, 16, v176
	v_and_b32_e32 v105, 0xffff0000, v176
	v_lshlrev_b32_e32 v106, 16, v177
	v_and_b32_e32 v107, 0xffff0000, v177
	v_lshlrev_b32_e32 v108, 16, v178
	v_and_b32_e32 v109, 0xffff0000, v178
	v_lshlrev_b32_e32 v110, 16, v179
	v_and_b32_e32 v111, 0xffff0000, v179
	v_lshlrev_b32_e32 v112, 16, v180
	v_and_b32_e32 v113, 0xffff0000, v180
	v_lshlrev_b32_e32 v114, 16, v181
	v_and_b32_e32 v115, 0xffff0000, v181
	v_lshlrev_b32_e32 v116, 16, v182
	v_and_b32_e32 v117, 0xffff0000, v182
	v_lshlrev_b32_e32 v118, 16, v183
	v_and_b32_e32 v119, 0xffff0000, v183
	v_pk_fma_f32 v[242:243], v[120:121], v[24:25], v[72:73]
	v_pk_fma_f32 v[224:225], v[128:129], v[32:33], v[80:81]
	v_pk_fma_f32 v[244:245], v[122:123], v[26:27], v[74:75]
	v_pk_fma_f32 v[226:227], v[130:131], v[34:35], v[82:83]
	v_pk_fma_f32 v[246:247], v[124:125], v[28:29], v[76:77]
	v_pk_fma_f32 v[228:229], v[132:133], v[36:37], v[84:85]
	v_pk_fma_f32 v[248:249], v[126:127], v[30:31], v[78:79]
	v_pk_fma_f32 v[230:231], v[134:135], v[38:39], v[86:87]
	v_pk_fma_f32 v[242:243], v[88:89], v[40:41], v[242:243]
	v_pk_fma_f32 v[224:225], v[96:97], v[48:49], v[224:225]
	v_pk_fma_f32 v[244:245], v[90:91], v[42:43], v[244:245]
	v_pk_fma_f32 v[226:227], v[98:99], v[50:51], v[226:227]
	v_pk_fma_f32 v[246:247], v[92:93], v[44:45], v[246:247]
	v_pk_fma_f32 v[228:229], v[100:101], v[52:53], v[228:229]
	v_pk_fma_f32 v[248:249], v[94:95], v[46:47], v[248:249]
	v_pk_fma_f32 v[230:231], v[102:103], v[54:55], v[230:231]
	v_pk_fma_f32 v[242:243], v[104:105], v[56:57], v[242:243]
	v_pk_fma_f32 v[224:225], v[112:113], v[64:65], v[224:225]
	v_pk_fma_f32 v[244:245], v[106:107], v[58:59], v[244:245]
	v_pk_fma_f32 v[226:227], v[114:115], v[66:67], v[226:227]
	v_pk_fma_f32 v[246:247], v[108:109], v[60:61], v[246:247]
	v_pk_fma_f32 v[228:229], v[116:117], v[68:69], v[228:229]
	v_pk_fma_f32 v[248:249], v[110:111], v[62:63], v[248:249]
	v_pk_fma_f32 v[230:231], v[118:119], v[70:71], v[230:231]
	v_pk_mul_f32 v[200:201], v[242:243], v[242:243]
	v_pk_mul_f32 v[202:203], v[244:245], v[244:245]
	v_pk_mul_f32 v[204:205], v[246:247], v[246:247]
	v_pk_mul_f32 v[206:207], v[248:249], v[248:249]
	v_pk_fma_f32 v[200:201], v[200:201], s[26:27], v[4:5]
	v_pk_fma_f32 v[202:203], v[202:203], s[26:27], v[4:5]
	v_pk_fma_f32 v[204:205], v[204:205], s[26:27], v[4:5]
	v_pk_fma_f32 v[206:207], v[206:207], s[26:27], v[4:5]
	v_pk_mul_f32 v[200:201], v[242:243], v[200:201]
	v_pk_mul_f32 v[202:203], v[244:245], v[202:203]
	v_pk_mul_f32 v[204:205], v[246:247], v[204:205]
	v_pk_mul_f32 v[206:207], v[248:249], v[206:207]
	v_exp_f32_e32 v200, v200
	v_exp_f32_e32 v201, v201
	v_exp_f32_e32 v202, v202
	v_exp_f32_e32 v203, v203
	v_exp_f32_e32 v204, v204
	v_exp_f32_e32 v205, v205
	v_exp_f32_e32 v206, v206
	v_exp_f32_e32 v207, v207
	v_pk_add_f32 v[200:201], v[200:201], s[28:29]
	v_pk_add_f32 v[202:203], v[202:203], s[28:29]
	v_pk_add_f32 v[204:205], v[204:205], s[28:29]
	v_pk_add_f32 v[206:207], v[206:207], s[28:29]
	v_rcp_f32_e32 v200, v200
	v_rcp_f32_e32 v201, v201
	v_rcp_f32_e32 v202, v202
	v_rcp_f32_e32 v203, v203
	v_rcp_f32_e32 v204, v204
	v_rcp_f32_e32 v205, v205
	v_rcp_f32_e32 v206, v206
	v_rcp_f32_e32 v207, v207
	v_pk_mul_f32 v[200:201], v[242:243], v[200:201]
	v_pk_mul_f32 v[202:203], v[244:245], v[202:203]
	v_pk_mul_f32 v[204:205], v[246:247], v[204:205]
	v_pk_mul_f32 v[206:207], v[248:249], v[206:207]
	v_pk_mul_f32 v[200:201], v[200:201], v[224:225]
	v_pk_mul_f32 v[202:203], v[202:203], v[226:227]
	v_pk_mul_f32 v[204:205], v[204:205], v[228:229]
	v_pk_mul_f32 v[206:207], v[206:207], v[230:231]
	v_cvt_pk_bf16_f32 v250, v200, v201
	v_cvt_pk_bf16_f32 v251, v202, v203
	v_cvt_pk_bf16_f32 v252, v204, v205
	v_cvt_pk_bf16_f32 v253, v206, v207
	global_store_dwordx4 v3, v[250:253], s[30:31]
	s_add_u32 s30, s30, 0x3000
	s_addc_u32 s31, s31, 0
	s_waitcnt vmcnt(2)
	v_lshlrev_b32_e32 v120, 16, v184
	v_and_b32_e32 v121, 0xffff0000, v184
	v_lshlrev_b32_e32 v122, 16, v185
	v_and_b32_e32 v123, 0xffff0000, v185
	v_lshlrev_b32_e32 v124, 16, v186
	v_and_b32_e32 v125, 0xffff0000, v186
	v_lshlrev_b32_e32 v126, 16, v187
	v_and_b32_e32 v127, 0xffff0000, v187
	v_lshlrev_b32_e32 v128, 16, v188
	v_and_b32_e32 v129, 0xffff0000, v188
	v_lshlrev_b32_e32 v130, 16, v189
	v_and_b32_e32 v131, 0xffff0000, v189
	v_lshlrev_b32_e32 v132, 16, v190
	v_and_b32_e32 v133, 0xffff0000, v190
	v_lshlrev_b32_e32 v134, 16, v191
	v_and_b32_e32 v135, 0xffff0000, v191
	v_pk_fma_f32 v[242:243], v[88:89], v[24:25], v[72:73]
	v_pk_fma_f32 v[224:225], v[96:97], v[32:33], v[80:81]
	v_pk_fma_f32 v[244:245], v[90:91], v[26:27], v[74:75]
	v_pk_fma_f32 v[226:227], v[98:99], v[34:35], v[82:83]
	v_pk_fma_f32 v[246:247], v[92:93], v[28:29], v[76:77]
	v_pk_fma_f32 v[228:229], v[100:101], v[36:37], v[84:85]
	v_pk_fma_f32 v[248:249], v[94:95], v[30:31], v[78:79]
	v_pk_fma_f32 v[230:231], v[102:103], v[38:39], v[86:87]
	v_pk_fma_f32 v[242:243], v[104:105], v[40:41], v[242:243]
	v_pk_fma_f32 v[224:225], v[112:113], v[48:49], v[224:225]
	v_pk_fma_f32 v[244:245], v[106:107], v[42:43], v[244:245]
	v_pk_fma_f32 v[226:227], v[114:115], v[50:51], v[226:227]
	v_pk_fma_f32 v[246:247], v[108:109], v[44:45], v[246:247]
	v_pk_fma_f32 v[228:229], v[116:117], v[52:53], v[228:229]
	v_pk_fma_f32 v[248:249], v[110:111], v[46:47], v[248:249]
	v_pk_fma_f32 v[230:231], v[118:119], v[54:55], v[230:231]
	v_pk_fma_f32 v[242:243], v[120:121], v[56:57], v[242:243]
	v_pk_fma_f32 v[224:225], v[128:129], v[64:65], v[224:225]
	v_pk_fma_f32 v[244:245], v[122:123], v[58:59], v[244:245]
	v_pk_fma_f32 v[226:227], v[130:131], v[66:67], v[226:227]
	v_pk_fma_f32 v[246:247], v[124:125], v[60:61], v[246:247]
; __device__ __forceinline__ u32x4 pack8(const float (&f)[8]) { u32x4 w; w.x = pk2(f[0], f[1]); w.y = pk2(f[2], f[3]); w.z = pk2(f[4], f[5]); w.w = pk2(f[6], f[7]); return w; }
; __device__ __forceinline__ float gelu_tanh(float x) { const float y = 1.5957691216f * (x + 0.044715f * x * x * x); return x * __builtin_amdgcn_rcpf(1.0f + __expf(-y)); }
; __device__ __forceinline__ void phase_ffnconv(const Params& p) {
;     ...
;         for (int rs = slot; rs < 1024; rs += 170) {
;             const int row = MPROMPT + rs, t = rs & 7, b = rs >> 3;
;             float xg[3][8], xv[3][8];
; #pragma unroll
;             for (int k = 0; k < 3; ++k) { const int tt = t - 2 + k;
;                 if (tt >= 0) { unpack8(*(const u32x4*)(UP + (size_t)(row - 2 + k) * 2 * DFF + colg), xg[k]); unpack8(*(const u32x4*)(UP + (size_t)(row - 2 + k) * 2 * DFF + colg + 128), xv[k]); }
;                 else { const float* sp = p.in[I_SFCONV] + ((size_t)b * 2 + (2 + tt)) * 2 * DFF; ld8f(sp + j0, xg[k]); ld8f(sp + DFF + j0, xv[k]); } }
;             float f[8];
; #pragma unroll
;             for (int e = 0; e < 8; ++e) { const float cg_ = bg[e] + xg[0][e] * wg[0][e] + xg[1][e] * wg[1][e] + xg[2][e] * wg[2][e];
;                 const float cv_ = bv[e] + xv[0][e] * wv[0][e] + xv[1][e] * wv[1][e] + xv[2][e] * wv[2][e]; f[e] = gelu_tanh(cg_) * cv_; }
;             *(u32x4*)(F + (size_t)row * DFF + j0) = pack8(f);
	v_pk_fma_f32 v[228:229], v[132:133], v[68:69], v[228:229]
	v_pk_fma_f32 v[248:249], v[126:127], v[62:63], v[248:249]
	v_pk_fma_f32 v[230:231], v[134:135], v[70:71], v[230:231]
	v_pk_mul_f32 v[200:201], v[242:243], v[242:243]
	v_pk_mul_f32 v[202:203], v[244:245], v[244:245]
	v_pk_mul_f32 v[204:205], v[246:247], v[246:247]
	v_pk_mul_f32 v[206:207], v[248:249], v[248:249]
	v_pk_fma_f32 v[200:201], v[200:201], s[26:27], v[4:5]
	v_pk_fma_f32 v[202:203], v[202:203], s[26:27], v[4:5]
	v_pk_fma_f32 v[204:205], v[204:205], s[26:27], v[4:5]
	v_pk_fma_f32 v[206:207], v[206:207], s[26:27], v[4:5]
	v_pk_mul_f32 v[200:201], v[242:243], v[200:201]
	v_pk_mul_f32 v[202:203], v[244:245], v[202:203]
	v_pk_mul_f32 v[204:205], v[246:247], v[204:205]
	v_pk_mul_f32 v[206:207], v[248:249], v[206:207]
	v_exp_f32_e32 v200, v200
	v_exp_f32_e32 v201, v201
	v_exp_f32_e32 v202, v202
	v_exp_f32_e32 v203, v203
	v_exp_f32_e32 v204, v204
	v_exp_f32_e32 v205, v205
	v_exp_f32_e32 v206, v206
	v_exp_f32_e32 v207, v207
	v_pk_add_f32 v[200:201], v[200:201], s[28:29]
	v_pk_add_f32 v[202:203], v[202:203], s[28:29]
	v_pk_add_f32 v[204:205], v[204:205], s[28:29]
	v_pk_add_f32 v[206:207], v[206:207], s[28:29]
	v_rcp_f32_e32 v200, v200
	v_rcp_f32_e32 v201, v201
	v_rcp_f32_e32 v202, v202
	v_rcp_f32_e32 v203, v203
	v_rcp_f32_e32 v204, v204
	v_rcp_f32_e32 v205, v205
	v_rcp_f32_e32 v206, v206
	v_rcp_f32_e32 v207, v207
	v_pk_mul_f32 v[200:201], v[242:243], v[200:201]
	v_pk_mul_f32 v[202:203], v[244:245], v[202:203]
	v_pk_mul_f32 v[204:205], v[246:247], v[204:205]
	v_pk_mul_f32 v[206:207], v[248:249], v[206:207]
	v_pk_mul_f32 v[200:201], v[200:201], v[224:225]
	v_pk_mul_f32 v[202:203], v[202:203], v[226:227]
	v_pk_mul_f32 v[204:205], v[204:205], v[228:229]
	v_pk_mul_f32 v[206:207], v[206:207], v[230:231]
	v_cvt_pk_bf16_f32 v250, v200, v201
	v_cvt_pk_bf16_f32 v251, v202, v203
	v_cvt_pk_bf16_f32 v252, v204, v205
	v_cvt_pk_bf16_f32 v253, v206, v207
	global_store_dwordx4 v3, v[250:253], s[30:31]
	s_add_u32 s30, s30, 0x3000
	s_addc_u32 s31, s31, 0
	s_waitcnt vmcnt(0)
	v_lshlrev_b32_e32 v88, 16, v192
	v_and_b32_e32 v89, 0xffff0000, v192
	v_lshlrev_b32_e32 v90, 16, v193
	v_and_b32_e32 v91, 0xffff0000, v193
	v_lshlrev_b32_e32 v92, 16, v194
	v_and_b32_e32 v93, 0xffff0000, v194
	v_lshlrev_b32_e32 v94, 16, v195
	v_and_b32_e32 v95, 0xffff0000, v195
	v_lshlrev_b32_e32 v96, 16, v196
	v_and_b32_e32 v97, 0xffff0000, v196
	v_lshlrev_b32_e32 v98, 16, v197
	v_and_b32_e32 v99, 0xffff0000, v197
	v_lshlrev_b32_e32 v100, 16, v198
	v_and_b32_e32 v101, 0xffff0000, v198
	v_lshlrev_b32_e32 v102, 16, v199
	v_and_b32_e32 v103, 0xffff0000, v199
	v_pk_fma_f32 v[242:243], v[104:105], v[24:25], v[72:73]
	v_pk_fma_f32 v[224:225], v[112:113], v[32:33], v[80:81]
	v_pk_fma_f32 v[244:245], v[106:107], v[26:27], v[74:75]
	v_pk_fma_f32 v[226:227], v[114:115], v[34:35], v[82:83]
	v_pk_fma_f32 v[246:247], v[108:109], v[28:29], v[76:77]
	v_pk_fma_f32 v[228:229], v[116:117], v[36:37], v[84:85]
	v_pk_fma_f32 v[248:249], v[110:111], v[30:31], v[78:79]
	v_pk_fma_f32 v[230:231], v[118:119], v[38:39], v[86:87]
	v_pk_fma_f32 v[242:243], v[120:121], v[40:41], v[242:243]
	v_pk_fma_f32 v[224:225], v[128:129], v[48:49], v[224:225]
	v_pk_fma_f32 v[244:245], v[122:123], v[42:43], v[244:245]
	v_pk_fma_f32 v[226:227], v[130:131], v[50:51], v[226:227]
	v_pk_fma_f32 v[246:247], v[124:125], v[44:45], v[246:247]
	v_pk_fma_f32 v[228:229], v[132:133], v[52:53], v[228:229]
	v_pk_fma_f32 v[248:249], v[126:127], v[46:47], v[248:249]
	v_pk_fma_f32 v[230:231], v[134:135], v[54:55], v[230:231]
	v_pk_fma_f32 v[242:243], v[88:89], v[56:57], v[242:243]
	v_pk_fma_f32 v[224:225], v[96:97], v[64:65], v[224:225]
	v_pk_fma_f32 v[244:245], v[90:91], v[58:59], v[244:245]
	v_pk_fma_f32 v[226:227], v[98:99], v[66:67], v[226:227]
	v_pk_fma_f32 v[246:247], v[92:93], v[60:61], v[246:247]
	v_pk_fma_f32 v[228:229], v[100:101], v[68:69], v[228:229]
	v_pk_fma_f32 v[248:249], v[94:95], v[62:63], v[248:249]
	v_pk_fma_f32 v[230:231], v[102:103], v[70:71], v[230:231]
	v_pk_mul_f32 v[200:201], v[242:243], v[242:243]
	v_pk_mul_f32 v[202:203], v[244:245], v[244:245]
	v_pk_mul_f32 v[204:205], v[246:247], v[246:247]
	v_pk_mul_f32 v[206:207], v[248:249], v[248:249]
	v_pk_fma_f32 v[200:201], v[200:201], s[26:27], v[4:5]
	v_pk_fma_f32 v[202:203], v[202:203], s[26:27], v[4:5]
	v_pk_fma_f32 v[204:205], v[204:205], s[26:27], v[4:5]
	v_pk_fma_f32 v[206:207], v[206:207], s[26:27], v[4:5]
	v_pk_mul_f32 v[200:201], v[242:243], v[200:201]
	v_pk_mul_f32 v[202:203], v[244:245], v[202:203]
	v_pk_mul_f32 v[204:205], v[246:247], v[204:205]
	v_pk_mul_f32 v[206:207], v[248:249], v[206:207]
	v_exp_f32_e32 v200, v200
	v_exp_f32_e32 v201, v201
	v_exp_f32_e32 v202, v202
	v_exp_f32_e32 v203, v203
	v_exp_f32_e32 v204, v204
	v_exp_f32_e32 v205, v205
	v_exp_f32_e32 v206, v206
	v_exp_f32_e32 v207, v207
	v_pk_add_f32 v[200:201], v[200:201], s[28:29]
	v_pk_add_f32 v[202:203], v[202:203], s[28:29]
	v_pk_add_f32 v[204:205], v[204:205], s[28:29]
	v_pk_add_f32 v[206:207], v[206:207], s[28:29]
	v_rcp_f32_e32 v200, v200
	v_rcp_f32_e32 v201, v201
	v_rcp_f32_e32 v202, v202
	v_rcp_f32_e32 v203, v203
	v_rcp_f32_e32 v204, v204
	v_rcp_f32_e32 v205, v205
	v_rcp_f32_e32 v206, v206
	v_rcp_f32_e32 v207, v207
	v_pk_mul_f32 v[200:201], v[242:243], v[200:201]
	v_pk_mul_f32 v[202:203], v[244:245], v[202:203]
	v_pk_mul_f32 v[204:205], v[246:247], v[204:205]
	v_pk_mul_f32 v[206:207], v[248:249], v[206:207]
	v_pk_mul_f32 v[200:201], v[200:201], v[224:225]
	v_pk_mul_f32 v[202:203], v[202:203], v[226:227]
	v_pk_mul_f32 v[204:205], v[204:205], v[228:229]
	v_pk_mul_f32 v[206:207], v[206:207], v[230:231]
	v_cvt_pk_bf16_f32 v250, v200, v201
	v_cvt_pk_bf16_f32 v251, v202, v203
	v_cvt_pk_bf16_f32 v252, v204, v205
	v_cvt_pk_bf16_f32 v253, v206, v207
	global_store_dwordx4 v3, v[250:253], s[30:31]
.Lp11_done:
	s_mov_b64 s[8:9], exec
